# Down GEMM split into latent pass + context pass; during the context pass the 224 idle workgroups run the next RMSNorm on latent rows, context rows normalised after, original norm phase skipped
# speedup vs baseline: 1.0150x; 1.0134x over previous
.LBB0_216:
	v_readlane_b32 s0, v254, 39
	v_readlane_b32 s1, v254, 40
	s_and_b64 s[0:1], s[0:1], s[6:7]
	s_and_b64 s[0:1], s[0:1], exec
	s_mov_b32 s0, 0x10000
	s_cselect_b32 s72, s0, 0x10800
	v_readlane_b32 s0, v255, 3
	s_or_b32 s0, s2, s0
	v_readlane_b32 s8, v253, 7
	v_mov_b32_e32 v1, v207
	s_cmp_eq_u32 s0, 0
	v_readlane_b32 s9, v253, 8
	v_readlane_b32 s12, v253, 11
	v_readlane_b32 s13, v253, 12
	s_cselect_b32 s65, s9, s49
	v_readfirstlane_b32 s0, v1
	s_cselect_b32 s68, s8, s48
	s_cselect_b32 s69, s13, s37
	s_cselect_b32 s70, s12, s33
	s_ashr_i32 s0, s0, 6
	v_readlane_b32 s1, v252, 34
	s_add_i32 s0, s0, s1
	v_readlane_b32 s1, v252, 54
	s_add_i32 s1, s1, s72
	s_ashr_i32 s3, s1, 31
	s_abs_i32 s1, s1
	v_readlane_b32 s6, v253, 59
	s_mul_hi_u32 s6, s1, s6
	v_readlane_b32 s9, v254, 21
	s_mul_i32 s7, s6, s9
	s_sub_i32 s1, s1, s7
	s_xor_b32 s3, s3, s91
	s_add_i32 s7, s6, 1
	s_sub_i32 s8, s1, s9
	s_cmp_ge_u32 s1, s9
	s_cselect_b32 s6, s7, s6
	s_cselect_b32 s1, s8, s1
	s_add_i32 s7, s6, 1
	s_cmp_ge_u32 s1, s9
	s_cselect_b32 s1, s7, s6
	s_xor_b32 s1, s1, s3
	s_sub_i32 s1, s1, s3
	s_mul_i32 s0, s1, s0
	v_readlane_b32 s10, v253, 9
	s_add_i32 s1, s0, s1
	v_readlane_b32 s22, v253, 21
	v_readlane_b32 s23, v253, 22
	s_min_i32 s10, s1, s72
	s_mov_b64 s[22:23], 0x1000
	s_cmp_ge_i32 s0, s10
	s_mul_i32 s6, s2, 0x1800
	v_readlane_b32 s11, v253, 10
	v_readlane_b32 s14, v253, 13
	v_readlane_b32 s15, v253, 14
	v_readlane_b32 s16, v253, 15
	v_readlane_b32 s17, v253, 16
	v_readlane_b32 s18, v253, 17
	v_readlane_b32 s19, v253, 18
	v_readlane_b32 s20, v253, 19
	v_readlane_b32 s21, v253, 20
	v_mov_b32_e32 v4, 0x20184
	ds_read_b32 v5, v4
	s_waitcnt lgkmcnt(0)
	s_barrier
	v_readfirstlane_b32 s98, v5
	s_cmp_eq_u32 s98, 0
	s_cbranch_scc1 .Lq_h1
	v_mov_b32_e32 v5, 0
	ds_write_b32 v4, v5
	s_branch .LBB0_221
.Lq_h1:
	s_cmp_ge_i32 s0, s10
	s_cbranch_scc1 .LBB0_221
	s_lshl_b32 s84, s2, 11
	s_lshl_b64 s[2:3], s[84:85], 2
	v_readlane_b32 s1, v255, 7
	s_add_u32 s2, s1, s2
	v_readlane_b32 s1, v255, 6
	s_addc_u32 s3, s1, s3
	s_add_i32 s11, s10, -1
	s_ashr_i32 s1, s0, 31
	s_add_i32 s7, s0, 0xffff0000
	s_cmp_gt_i32 s0, 0xffff
	s_cselect_b32 s9, 0, s1
	s_cselect_b32 s8, s7, s0
	s_cselect_b32 s7, s69, s65
	s_cselect_b32 s12, s70, s68
	s_lshl_b64 s[8:9], s[8:9], 12
	s_add_u32 s8, s12, s8
	v_and_b32_e32 v84, 63, v1
	s_addc_u32 s9, s7, s9
	s_add_i32 s7, s0, 1
	v_lshlrev_b32_e32 v36, 4, v84
	s_min_i32 s7, s7, s11
	global_load_dwordx4 v[8:11], v36, s[8:9] offset:3072 nt
	global_load_dwordx4 v[4:7], v36, s[8:9] offset:2048 nt
	global_load_dwordx4 v[24:27], v36, s[8:9] nt
	global_load_dwordx4 v[20:23], v36, s[8:9] offset:1024 nt
	s_ashr_i32 s8, s7, 31
	s_add_i32 s12, s7, 0xffff0000
	s_cmp_gt_i32 s7, 0xffff
	s_cselect_b32 s9, 0, s8
	s_cselect_b32 s8, s12, s7
	s_cselect_b32 s7, s69, s65
	s_cselect_b32 s12, s70, s68
	s_lshl_b64 s[8:9], s[8:9], 12
	s_add_u32 s8, s12, s8
	s_addc_u32 s9, s7, s9
	global_load_dwordx4 v[16:19], v36, s[8:9] offset:3072 nt
	global_load_dwordx4 v[12:15], v36, s[8:9] offset:2048 nt
	global_load_dwordx4 v[28:31], v36, s[8:9] offset:1024 nt
	global_load_dwordx4 v[32:35], v36, s[8:9] nt
	v_cmp_lt_i32_e32 vcc, v228, v235
	v_mov_b32_e32 v37, v0
	s_mov_b32 s7, s85
	v_cndmask_b32_e32 v38, v233, v228, vcc
	v_cmp_lt_i32_e32 vcc, v234, v235
	v_lshl_add_u64 v[86:87], s[2:3], 0, v[36:37]
	s_lshl_b64 s[2:3], s[6:7], 2
	v_cndmask_b32_e32 v40, v233, v234, vcc
	v_cmp_lt_i32_e32 vcc, v240, v235
	v_readlane_b32 s7, v255, 10
	s_add_u32 s7, s7, s2
	v_cndmask_b32_e32 v41, v233, v240, vcc
	v_cmp_lt_i32_e32 vcc, v245, v235
	v_readlane_b32 s2, v255, 12
	s_addc_u32 s8, s2, s3
	v_cndmask_b32_e32 v42, v233, v245, vcc
	v_cmp_lt_i32_e32 vcc, v246, v235
	s_lshl_b64 s[2:3], s[0:1], 11
	v_mov_b32_e32 v2, v0
	v_cndmask_b32_e32 v43, v233, v246, vcc
	v_cmp_lt_i32_e32 vcc, v241, v235
	v_mov_b32_e32 v3, v0
	s_add_u32 s2, s96, s2
	v_readlane_b32 s1, v252, 53
	v_cndmask_b32_e32 v44, v233, v241, vcc
	v_mov_b32_e32 v39, v0
	v_mov_b32_e32 v1, v0
	v_lshlrev_b32_e32 v85, 2, v38
	v_lshlrev_b32_e32 v38, 3, v84
	s_waitcnt vmcnt(16)
	v_mov_b64_e32 v[66:67], v[2:3]
	s_addc_u32 s3, s1, s3
	v_mov_b64_e32 v[78:79], v[2:3]
	v_mov_b64_e32 v[74:75], v[2:3]
	v_mov_b64_e32 v[82:83], v[2:3]
	v_mov_b64_e32 v[70:71], v[2:3]
	v_mov_b64_e32 v[54:55], v[2:3]
	v_mov_b64_e32 v[58:59], v[2:3]
	v_mov_b64_e32 v[62:63], v[2:3]
	s_mov_b32 s9, -1
	v_lshlrev_b32_e32 v90, 2, v40
	v_lshlrev_b32_e32 v91, 2, v41
	v_lshlrev_b32_e32 v92, 2, v42
	v_lshlrev_b32_e32 v93, 2, v43
	v_lshlrev_b32_e32 v94, 2, v44
	v_mov_b64_e32 v[64:65], v[0:1]
	v_lshl_add_u64 v[88:89], s[2:3], 0, v[38:39]
	v_mov_b64_e32 v[76:77], v[0:1]
	v_mov_b64_e32 v[72:73], v[0:1]
	v_mov_b64_e32 v[80:81], v[0:1]
	v_mov_b64_e32 v[68:69], v[0:1]
	v_mov_b64_e32 v[52:53], v[0:1]
	v_mov_b64_e32 v[56:57], v[0:1]
	v_mov_b64_e32 v[60:61], v[0:1]
	s_waitcnt vmcnt(7)
	v_mov_b32_e32 v95, v8
	v_mov_b32_e32 v96, v9
	v_mov_b32_e32 v97, v10
	v_mov_b32_e32 v98, v11
	s_branch .LBB0_219

.LBB0_346:
	s_or_b64 exec, exec, s[0:1]
	v_mov_b32_e32 v14, v207
	s_lshr_b32 s84, s72, 6
	s_waitcnt lgkmcnt(0)
	s_barrier
	v_mov_b32_e32 v4, 0x20180
	ds_read_b32 v5, v4
	s_waitcnt lgkmcnt(0)
	s_barrier
	v_readfirstlane_b32 s98, v5
	s_cmp_lg_u32 s98, 0
	s_cbranch_scc1 .Lq_dn
	s_cmp_lg_u32 s72, 0x10800
	s_cbranch_scc1 .Lq_dn
	v_mov_b32_e32 v5, 1
	ds_write_b32 v4, v5
	s_mov_b32 s72, 0x10000
	s_movk_i32 s71, 0x100
	s_movk_i32 s84, 0x400
.Lq_dn:
	s_movk_i32 s0, 0xb00
	s_cmp_ge_i32 s24, s84
	v_readfirstlane_b32 s2, v14
	s_cbranch_scc1 .Lq_idle
	v_lshlrev_b32_e32 v1, 4, v14
	v_add_u32_e32 v2, 0x2000, v1
	v_ashrrev_i32_e32 v3, 31, v2
	v_lshrrev_b32_e32 v3, 22, v3
	v_add_u32_e32 v3, v2, v3
	v_ashrrev_i32_e32 v3, 10, v3
	v_mul_i32_i24_e32 v4, 0x400, v3
	v_sub_u32_e32 v2, v2, v4
	v_lshrrev_b32_e32 v4, 4, v2
	v_bitop3_b32 v4, v4, v2, 32 bitop3:0x6c
	v_ashrrev_i32_e32 v2, 31, v4
	v_lshrrev_b32_e32 v2, 26, v2
	v_add_u32_e32 v5, v4, v2
	v_lshlrev_b32_e32 v6, 3, v3
	v_ashrrev_i32_e32 v2, 6, v5
	v_and_b32_e32 v6, 0x7ffffff0, v6
	v_add_u32_e32 v6, v2, v6
	v_lshlrev_b32_e32 v2, 5, v3
	v_and_b32_e32 v2, 32, v2
	v_mad_u64_u32 v[2:3], s[14:15], v6, s0, v[2:3]
	v_and_b32_e32 v3, 0xc0, v5
	v_sub_u32_e32 v3, v4, v3
	v_ashrrev_i16_sdwa v3, v230, sext(v3) dst_sel:DWORD dst_unused:UNUSED_PAD src0_sel:DWORD src1_sel:BYTE_0
	v_bfe_i32 v3, v3, 0, 16
	v_add_lshl_u32 v130, v2, v3, 1
	v_bfe_i32 v2, v14, 27, 1
	v_lshrrev_b32_e32 v2, 22, v2
	v_add_u32_e32 v2, v1, v2
	v_and_b32_e32 v2, 0xfffffc00, v2
	v_sub_u32_e32 v1, v1, v2
	v_lshrrev_b32_e32 v2, 4, v1
	v_ashrrev_i32_e32 v3, 31, v14
	v_bitop3_b32 v1, v2, v1, 32 bitop3:0x6c
	v_lshrrev_b32_e32 v3, 26, v3
	v_ashrrev_i32_e32 v2, 31, v1
	v_add_u32_e32 v3, v14, v3
	s_and_b64 s[8:9], s[4:5], exec
	v_lshrrev_b32_e32 v2, 26, v2
	v_ashrrev_i32_e32 v3, 6, v3
	v_readlane_b32 s8, v255, 4
	v_add_u32_e32 v4, v1, v2
	v_lshlrev_b32_e32 v5, 3, v3
	s_mov_b32 s1, 0xb10000
	s_mov_b32 s3, 0x2c10000
	v_readlane_b32 s9, v255, 5
	v_ashrrev_i32_e32 v2, 6, v4
	v_and_b32_e32 v5, 0x7ffffff0, v5
	s_cselect_b32 s1, s1, 0x1b90000
	s_cselect_b32 s3, s3, 0x3c90000
	s_and_b64 s[8:9], s[8:9], exec
	v_add_u32_e32 v5, v2, v5
	v_lshlrev_b32_e32 v2, 5, v3
	s_cselect_b32 s1, s1, s3
	v_and_b32_e32 v2, 32, v2
	s_add_u32 s52, s50, s1
	v_mad_u64_u32 v[2:3], s[14:15], v5, s0, v[2:3]
	s_addc_u32 s53, s51, 0
	s_ashr_i32 s3, s2, 6
	s_ashr_i32 s1, s0, 31
	s_lshr_b32 s57, s72, 9
	v_readlane_b32 s14, v253, 55
	s_ashr_i32 s10, s2, 8
	s_lshl_b64 s[8:9], s[0:1], 8
	s_lshl_b64 s[12:13], s[0:1], 9
	s_lshl_b32 s56, s3, 10
	s_or_b32 s66, s57, 1
	v_readlane_b32 s15, v253, 56
	s_and_b64 s[14:15], s[14:15], exec
	s_cselect_b32 s7, s66, s57
	v_readlane_b32 s11, v253, 57
	s_mul_i32 s7, s7, s11
	v_readlane_b32 s11, v253, 58
	s_add_i32 s7, s7, s11
	s_ashr_i32 s11, s7, 31
	s_lshr_b32 s11, s11, 27
	s_add_i32 s11, s7, s11
	s_ashr_i32 s14, s11, 5
	v_and_b32_e32 v3, 0xc0, v4
	s_lshl_b32 s14, s14, 3
	v_sub_u32_e32 v1, v1, v3
	s_sub_i32 s15, s71, s14
	v_ashrrev_i16_sdwa v1, v230, sext(v1) dst_sel:DWORD dst_unused:UNUSED_PAD src0_sel:DWORD src1_sel:BYTE_0
	s_min_i32 s15, s15, 8
	v_bfe_i32 v1, v1, 0, 16
	s_abs_i32 s17, s15
	v_add_lshl_u32 v132, v2, v1, 1
	v_cvt_f32_u32_e32 v1, s17
	s_sub_i32 s18, 0, s17
	s_andn2_b32 s11, s11, 31
	s_sub_i32 s7, s7, s11
	v_rcp_iflag_f32_e32 v1, v1
	s_abs_i32 s16, s7
	s_xor_b32 s11, s7, s15
	s_ashr_i32 s11, s11, 31
	v_mul_f32_e32 v1, 0x4f7ffffe, v1
	v_cvt_u32_f32_e32 v1, v1
	v_mov_b32_e32 v133, v0
	v_mov_b32_e32 v131, v0
	v_readfirstlane_b32 s19, v1
	s_mul_i32 s18, s18, s19
	s_mul_hi_u32 s18, s19, s18
	s_add_i32 s19, s19, s18
	s_mul_hi_u32 s18, s16, s19
	s_mul_i32 s19, s18, s17
	s_sub_i32 s16, s16, s19
	s_add_i32 s19, s18, 1
	s_sub_i32 s20, s16, s17
	s_cmp_ge_u32 s16, s17
	s_cselect_b32 s18, s19, s18
	s_cselect_b32 s16, s20, s16
	s_add_i32 s19, s18, 1
	s_cmp_ge_u32 s16, s17
	s_cselect_b32 s16, s19, s18
	s_xor_b32 s16, s16, s11
	s_sub_i32 s92, s16, s11
	s_mul_i32 s11, s92, s15
	s_sub_i32 s7, s7, s11
	s_add_i32 s11, s14, s7
	s_ashr_i32 s7, s11, 31
	s_mul_i32 s7, s12, s7
	s_mul_hi_u32 s14, s12, s11
	s_add_i32 s7, s14, s7
	s_lshr_b64 s[14:15], s[0:1], 23
	s_mul_i32 s15, s14, s11
	s_add_i32 s7, s7, s15
	s_ashr_i32 s15, s92, 31
	s_mul_i32 s15, s12, s15
	s_mul_hi_u32 s17, s12, s92
	s_add_i32 s15, s17, s15
	s_mul_i32 s14, s14, s92
	s_add_i32 s15, s15, s14
	s_mul_i32 s14, s12, s92
	s_add_u32 s22, s52, s14
	s_addc_u32 s23, s53, s15
	s_add_i32 s67, s56, 0
	s_add_i32 m0, s67, 0x10000
	s_mul_i32 s16, s12, s11
	global_load_lds_dwordx4 v132, s[22:23]
	s_add_i32 m0, s67, 0x12000
	s_add_u32 s14, s22, s8
	global_load_lds_dwordx4 v130, s[22:23]
	s_addc_u32 s15, s23, s9
	s_add_i32 m0, s67, 0x14000
	v_lshl_add_u64 v[6:7], s[14:15], 0, v[132:133]
	global_load_lds_dwordx4 v132, s[14:15]
	s_add_i32 m0, s67, 0x16000
	s_add_u32 s20, s34, s16
	s_addc_u32 s21, s35, s7
	s_add_i32 s72, s67, 0x2000
	v_lshl_add_u64 v[8:9], s[14:15], 0, v[130:131]
	global_load_lds_dwordx4 v130, s[14:15]
	s_mov_b32 m0, s67
	s_add_u32 s14, s20, s8
	global_load_lds_dwordx4 v132, s[20:21]
	s_mov_b32 m0, s72
	s_addc_u32 s15, s21, s9
	s_add_i32 s73, s67, 0x4000
	global_load_lds_dwordx4 v130, s[20:21]
	s_mov_b32 m0, s73
	s_add_i32 s74, s67, 0x6000
	global_load_lds_dwordx4 v132, s[14:15]
	s_mov_b32 m0, s74
	s_cmp_eq_u32 s10, 1
	global_load_lds_dwordx4 v130, s[14:15]
	v_lshl_add_u64 v[2:3], s[22:23], 0, v[132:133]
	v_lshl_add_u64 v[4:5], s[22:23], 0, v[130:131]
	v_lshl_add_u64 v[10:11], s[20:21], 0, v[132:133]
	v_lshl_add_u64 v[12:13], s[20:21], 0, v[130:131]
	s_cselect_b64 s[14:15], -1, 0
	s_cmp_lg_u32 s10, 1
	s_cbranch_scc1 .LBB0_349
	s_barrier

.Lq_idle:
	v_mov_b32_e32 v4, 0x20180
	ds_read_b32 v5, v4
	s_waitcnt lgkmcnt(0)
	v_readfirstlane_b32 s98, v5
	s_cmp_eq_u32 s98, 2
	s_cbranch_scc0 .Lq_idle_out
	s_ashr_i32 s0, s2, 6
	s_add_i32 s1, s24, -32
	s_lshl_b32 s1, s1, 3
	s_add_i32 s0, s0, s1
	s_mul_i32 s0, s0, 37
	s_add_i32 s10, s0, 37
	s_min_i32 s10, s10, 0x10000
	s_cmp_ge_i32 s0, s10
	s_cbranch_scc1 .Lq_idle_out
	v_readlane_b32 s12, v252, 53
	v_and_b32_e32 v1, 63, v207
	v_lshlrev_b32_e32 v84, 4, v1
	v_lshlrev_b32_e32 v85, 3, v1
	v_xor_b32_e32 v86, 1, v1
	v_lshlrev_b32_e32 v86, 2, v86
	v_xor_b32_e32 v87, 2, v1
	v_lshlrev_b32_e32 v87, 2, v87
	v_xor_b32_e32 v88, 4, v1
	v_lshlrev_b32_e32 v88, 2, v88
	v_xor_b32_e32 v89, 8, v1
	v_lshlrev_b32_e32 v89, 2, v89
	v_xor_b32_e32 v90, 16, v1
	v_lshlrev_b32_e32 v90, 2, v90
	v_xor_b32_e32 v91, 32, v1
	v_lshlrev_b32_e32 v91, 2, v91
	s_add_i32 s11, s10, -1
	s_mov_b32 s9, -1
	s_add_i32 s1, s0, 0
	s_min_i32 s1, s1, s11
	s_add_i32 s8, s1, 0xffff0000
	s_cmp_gt_i32 s1, 0xffff
	s_cselect_b32 s1, s8, s1
	s_cselect_b32 s2, s48, s33
	s_cselect_b32 s3, s49, s37
	s_lshl_b32 s8, s1, 12
	s_add_u32 s2, s2, s8
	s_addc_u32 s3, s3, 0
	global_load_dwordx4 v[4:7], v84, s[2:3] nt
	global_load_dwordx4 v[8:11], v84, s[2:3] offset:1024 nt
	global_load_dwordx4 v[12:15], v84, s[2:3] offset:2048 nt
	global_load_dwordx4 v[16:19], v84, s[2:3] offset:3072 nt
	s_add_i32 s1, s0, 1
	s_min_i32 s1, s1, s11
	s_add_i32 s8, s1, 0xffff0000
	s_cmp_gt_i32 s1, 0xffff
	s_cselect_b32 s1, s8, s1
	s_cselect_b32 s2, s48, s33
	s_cselect_b32 s3, s49, s37
	s_lshl_b32 s8, s1, 12
	s_add_u32 s2, s2, s8
	s_addc_u32 s3, s3, 0
	global_load_dwordx4 v[20:23], v84, s[2:3] nt
	global_load_dwordx4 v[24:27], v84, s[2:3] offset:1024 nt
	global_load_dwordx4 v[28:31], v84, s[2:3] offset:2048 nt
	global_load_dwordx4 v[32:35], v84, s[2:3] offset:3072 nt
	s_add_i32 s1, s0, 2
	s_min_i32 s1, s1, s11
	s_add_i32 s8, s1, 0xffff0000
	s_cmp_gt_i32 s1, 0xffff
	s_cselect_b32 s1, s8, s1
	s_cselect_b32 s2, s48, s33
	s_cselect_b32 s3, s49, s37
	s_lshl_b32 s8, s1, 12
	s_add_u32 s2, s2, s8
	s_addc_u32 s3, s3, 0
	global_load_dwordx4 v[36:39], v84, s[2:3] nt
	global_load_dwordx4 v[40:43], v84, s[2:3] offset:1024 nt
	global_load_dwordx4 v[44:47], v84, s[2:3] offset:2048 nt
	global_load_dwordx4 v[48:51], v84, s[2:3] offset:3072 nt
	s_add_i32 s1, s0, 3
	s_min_i32 s1, s1, s11
	s_add_i32 s8, s1, 0xffff0000
	s_cmp_gt_i32 s1, 0xffff
	s_cselect_b32 s1, s8, s1
	s_cselect_b32 s2, s48, s33
	s_cselect_b32 s3, s49, s37
	s_lshl_b32 s8, s1, 12
	s_add_u32 s2, s2, s8
	s_addc_u32 s3, s3, 0
	global_load_dwordx4 v[52:55], v84, s[2:3] nt
	global_load_dwordx4 v[56:59], v84, s[2:3] offset:1024 nt
	global_load_dwordx4 v[60:63], v84, s[2:3] offset:2048 nt
	global_load_dwordx4 v[64:67], v84, s[2:3] offset:3072 nt
.LnormQ1_p0:
	s_cmp_ge_i32 s0, s10
	s_cbranch_scc1 .LnormQ1_done
	s_min_i32 s1, s0, 0x10000
	s_ashr_i32 s1, s1, 13
	s_cmp_eq_u32 s1, s9
	s_cbranch_scc1 .LnormQ1_p0_go
	s_mov_b32 s9, s1
	v_readlane_b32 s2, v255, 7
	v_readlane_b32 s3, v255, 6
	s_add_u32 s2, s2, 0x1000
	s_addc_u32 s3, s3, 0
	s_cmp_lg_u32 s4, 0
	s_cbranch_scc1 .Lq_ng_Q1_p0
	v_readlane_b32 s2, v252, 2
	v_readlane_b32 s3, v252, 3
	s_nop 4
.Lq_ng_Q1_p0:
	global_load_dwordx4 v[68:71], v84, s[2:3]
	global_load_dwordx4 v[72:75], v84, s[2:3] offset:1024
	global_load_dwordx4 v[76:79], v84, s[2:3] offset:2048
	global_load_dwordx4 v[80:83], v84, s[2:3] offset:3072
	v_readlane_b32 s2, v255, 10
	v_readlane_b32 s3, v255, 12
	s_add_u32 s2, s2, 0x3000
	s_addc_u32 s3, s3, 0
	s_cmp_lg_u32 s4, 0
	s_cbranch_scc1 .Lq_md_Q1_p0
	v_readlane_b32 s2, v252, 51
	v_readlane_b32 s3, v252, 52
	s_add_u32 s2, s2, 0x51000
	s_addc_u32 s3, s3, 0
.Lq_md_Q1_p0:
	s_mul_i32 s8, s1, 0x9000
	s_add_u32 s2, s2, s8
	s_addc_u32 s3, s3, 0
	global_load_dwordx4 v[100:103], v84, s[2:3]
	global_load_dwordx4 v[104:107], v84, s[2:3] offset:1024
	global_load_dwordx4 v[108:111], v84, s[2:3] offset:2048
	global_load_dwordx4 v[112:115], v84, s[2:3] offset:3072
	s_add_u32 s2, s2, 0x1000
	s_addc_u32 s3, s3, 0
	global_load_dwordx4 v[116:119], v84, s[2:3]
	s_waitcnt vmcnt(0)
	v_add_f32_e32 v116, 1.0, v116
	v_add_f32_e32 v117, 1.0, v117
	v_add_f32_e32 v118, 1.0, v118
	v_add_f32_e32 v119, 1.0, v119
	v_mul_f32_e32 v68, v68, v116
	v_mul_f32_e32 v69, v69, v117
	v_mul_f32_e32 v70, v70, v118
	v_mul_f32_e32 v71, v71, v119
	global_load_dwordx4 v[116:119], v84, s[2:3] offset:1024
	s_waitcnt vmcnt(0)
	v_add_f32_e32 v116, 1.0, v116
	v_add_f32_e32 v117, 1.0, v117
	v_add_f32_e32 v118, 1.0, v118
	v_add_f32_e32 v119, 1.0, v119
	v_mul_f32_e32 v72, v72, v116
	v_mul_f32_e32 v73, v73, v117
	v_mul_f32_e32 v74, v74, v118
	v_mul_f32_e32 v75, v75, v119
	global_load_dwordx4 v[116:119], v84, s[2:3] offset:2048
	s_waitcnt vmcnt(0)
	v_add_f32_e32 v116, 1.0, v116
	v_add_f32_e32 v117, 1.0, v117
	v_add_f32_e32 v118, 1.0, v118
	v_add_f32_e32 v119, 1.0, v119
	v_mul_f32_e32 v76, v76, v116
	v_mul_f32_e32 v77, v77, v117
	v_mul_f32_e32 v78, v78, v118
	v_mul_f32_e32 v79, v79, v119
	global_load_dwordx4 v[116:119], v84, s[2:3] offset:3072
	s_waitcnt vmcnt(0)
	v_add_f32_e32 v116, 1.0, v116
	v_add_f32_e32 v117, 1.0, v117
	v_add_f32_e32 v118, 1.0, v118
	v_add_f32_e32 v119, 1.0, v119
	v_mul_f32_e32 v80, v80, v116
	v_mul_f32_e32 v81, v81, v117
	v_mul_f32_e32 v82, v82, v118
	v_mul_f32_e32 v83, v83, v119
.LnormQ1_p0_go:
	s_waitcnt vmcnt(12)
	v_mul_f32_e32 v92, v4, v4
	v_fmac_f32_e32 v92, v5, v5
	v_mul_f32_e32 v95, v6, v6
	v_fmac_f32_e32 v95, v7, v7
	v_add_f32_e32 v92, v92, v95
	v_mul_f32_e32 v93, v8, v8
	v_fmac_f32_e32 v93, v9, v9
	v_mul_f32_e32 v95, v10, v10
	v_fmac_f32_e32 v95, v11, v11
	v_add_f32_e32 v93, v93, v95
	v_add_f32_e32 v92, v92, v93
	v_mul_f32_e32 v93, v12, v12
	v_fmac_f32_e32 v93, v13, v13
	v_mul_f32_e32 v95, v14, v14
	v_fmac_f32_e32 v95, v15, v15
	v_add_f32_e32 v93, v93, v95
	v_add_f32_e32 v92, v92, v93
	v_mul_f32_e32 v93, v16, v16
	v_fmac_f32_e32 v93, v17, v17
	v_mul_f32_e32 v95, v18, v18
	v_fmac_f32_e32 v95, v19, v19
	v_add_f32_e32 v93, v93, v95
	v_add_f32_e32 v92, v92, v93
	ds_bpermute_b32 v93, v86, v92
	s_waitcnt lgkmcnt(0)
	v_add_f32_e32 v92, v92, v93
	ds_bpermute_b32 v93, v87, v92
	s_waitcnt lgkmcnt(0)
	v_add_f32_e32 v92, v92, v93
	ds_bpermute_b32 v93, v88, v92
	s_waitcnt lgkmcnt(0)
	v_add_f32_e32 v92, v92, v93
	ds_bpermute_b32 v93, v89, v92
	s_waitcnt lgkmcnt(0)
	v_add_f32_e32 v92, v92, v93
	ds_bpermute_b32 v93, v90, v92
	s_waitcnt lgkmcnt(0)
	v_add_f32_e32 v92, v92, v93
	ds_bpermute_b32 v93, v91, v92
	s_waitcnt lgkmcnt(0)
	v_add_f32_e32 v92, v92, v93
	v_fmamk_f32 v92, v92, 0x3a800000, v206
	v_rsq_f32_e32 v94, v92
	s_lshl_b32 s1, s0, 11
	s_add_u32 s98, s96, s1
	s_addc_u32 s99, s12, 0
	v_mul_f32_e32 v1, v4, v94
	v_mul_f32_e32 v2, v5, v94
	v_mul_f32_e32 v3, v6, v94
	v_mul_f32_e32 v93, v7, v94
	v_fma_f32 v1, v68, v1, v100
	v_fma_f32 v2, v69, v2, v101
	v_fma_f32 v3, v70, v3, v102
	v_fma_f32 v93, v71, v93, v103
	v_cvt_pk_bf16_f32 v116, v1, v2
	v_cvt_pk_bf16_f32 v117, v3, v93
	global_store_dwordx2 v85, v[116:117], s[98:99]
	v_mul_f32_e32 v1, v8, v94
	v_mul_f32_e32 v2, v9, v94
	v_mul_f32_e32 v3, v10, v94
	v_mul_f32_e32 v93, v11, v94
	v_fma_f32 v1, v72, v1, v104
	v_fma_f32 v2, v73, v2, v105
	v_fma_f32 v3, v74, v3, v106
	v_fma_f32 v93, v75, v93, v107
	v_cvt_pk_bf16_f32 v118, v1, v2
	v_cvt_pk_bf16_f32 v119, v3, v93
	global_store_dwordx2 v85, v[118:119], s[98:99] offset:512
	v_mul_f32_e32 v1, v12, v94
	v_mul_f32_e32 v2, v13, v94
	v_mul_f32_e32 v3, v14, v94
	v_mul_f32_e32 v93, v15, v94
	v_fma_f32 v1, v76, v1, v108
	v_fma_f32 v2, v77, v2, v109
	v_fma_f32 v3, v78, v3, v110
	v_fma_f32 v93, v79, v93, v111
	v_cvt_pk_bf16_f32 v120, v1, v2
	v_cvt_pk_bf16_f32 v121, v3, v93
	global_store_dwordx2 v85, v[120:121], s[98:99] offset:1024
	v_mul_f32_e32 v1, v16, v94
	v_mul_f32_e32 v2, v17, v94
	v_mul_f32_e32 v3, v18, v94
	v_mul_f32_e32 v93, v19, v94
	v_fma_f32 v1, v80, v1, v112
	v_fma_f32 v2, v81, v2, v113
	v_fma_f32 v3, v82, v3, v114
	v_fma_f32 v93, v83, v93, v115
	v_cvt_pk_bf16_f32 v96, v1, v2
	v_cvt_pk_bf16_f32 v97, v3, v93
	global_store_dwordx2 v85, v[96:97], s[98:99] offset:1536
	s_add_i32 s1, s0, 4
	s_min_i32 s1, s1, s11
	s_add_i32 s8, s1, 0xffff0000
	s_cmp_gt_i32 s1, 0xffff
	s_cselect_b32 s1, s8, s1
	s_cselect_b32 s2, s48, s33
	s_cselect_b32 s3, s49, s37
	s_lshl_b32 s8, s1, 12
	s_add_u32 s2, s2, s8
	s_addc_u32 s3, s3, 0
	global_load_dwordx4 v[4:7], v84, s[2:3] nt
	global_load_dwordx4 v[8:11], v84, s[2:3] offset:1024 nt
	global_load_dwordx4 v[12:15], v84, s[2:3] offset:2048 nt
	global_load_dwordx4 v[16:19], v84, s[2:3] offset:3072 nt
	s_add_i32 s0, s0, 1

.LnormQ1_p1_go:
	s_waitcnt vmcnt(16)
	v_mul_f32_e32 v92, v20, v20
	v_fmac_f32_e32 v92, v21, v21
	v_mul_f32_e32 v95, v22, v22
	v_fmac_f32_e32 v95, v23, v23
	v_add_f32_e32 v92, v92, v95
	v_mul_f32_e32 v93, v24, v24
	v_fmac_f32_e32 v93, v25, v25
	v_mul_f32_e32 v95, v26, v26
	v_fmac_f32_e32 v95, v27, v27
	v_add_f32_e32 v93, v93, v95
	v_add_f32_e32 v92, v92, v93
	v_mul_f32_e32 v93, v28, v28
	v_fmac_f32_e32 v93, v29, v29
	v_mul_f32_e32 v95, v30, v30
	v_fmac_f32_e32 v95, v31, v31
	v_add_f32_e32 v93, v93, v95
	v_add_f32_e32 v92, v92, v93
	v_mul_f32_e32 v93, v32, v32
	v_fmac_f32_e32 v93, v33, v33
	v_mul_f32_e32 v95, v34, v34
	v_fmac_f32_e32 v95, v35, v35
	v_add_f32_e32 v93, v93, v95
	v_add_f32_e32 v92, v92, v93
	ds_bpermute_b32 v93, v86, v92
	s_waitcnt lgkmcnt(0)
	v_add_f32_e32 v92, v92, v93
	ds_bpermute_b32 v93, v87, v92
	s_waitcnt lgkmcnt(0)
	v_add_f32_e32 v92, v92, v93
	ds_bpermute_b32 v93, v88, v92
	s_waitcnt lgkmcnt(0)
	v_add_f32_e32 v92, v92, v93
	ds_bpermute_b32 v93, v89, v92
	s_waitcnt lgkmcnt(0)
	v_add_f32_e32 v92, v92, v93
	ds_bpermute_b32 v93, v90, v92
	s_waitcnt lgkmcnt(0)
	v_add_f32_e32 v92, v92, v93
	ds_bpermute_b32 v93, v91, v92
	s_waitcnt lgkmcnt(0)
	v_add_f32_e32 v92, v92, v93
	v_fmamk_f32 v92, v92, 0x3a800000, v206
	v_rsq_f32_e32 v94, v92
	s_lshl_b32 s1, s0, 11
	s_add_u32 s98, s96, s1
	s_addc_u32 s99, s12, 0
	v_mul_f32_e32 v1, v20, v94
	v_mul_f32_e32 v2, v21, v94
	v_mul_f32_e32 v3, v22, v94
	v_mul_f32_e32 v93, v23, v94
	v_fma_f32 v1, v68, v1, v100
	v_fma_f32 v2, v69, v2, v101
	v_fma_f32 v3, v70, v3, v102
	v_fma_f32 v93, v71, v93, v103
	v_cvt_pk_bf16_f32 v116, v1, v2
	v_cvt_pk_bf16_f32 v117, v3, v93
	global_store_dwordx2 v85, v[116:117], s[98:99]
	v_mul_f32_e32 v1, v24, v94
	v_mul_f32_e32 v2, v25, v94
	v_mul_f32_e32 v3, v26, v94
	v_mul_f32_e32 v93, v27, v94
	v_fma_f32 v1, v72, v1, v104
	v_fma_f32 v2, v73, v2, v105
	v_fma_f32 v3, v74, v3, v106
	v_fma_f32 v93, v75, v93, v107
	v_cvt_pk_bf16_f32 v118, v1, v2
	v_cvt_pk_bf16_f32 v119, v3, v93
	global_store_dwordx2 v85, v[118:119], s[98:99] offset:512
	v_mul_f32_e32 v1, v28, v94
	v_mul_f32_e32 v2, v29, v94
	v_mul_f32_e32 v3, v30, v94
	v_mul_f32_e32 v93, v31, v94
	v_fma_f32 v1, v76, v1, v108
	v_fma_f32 v2, v77, v2, v109
	v_fma_f32 v3, v78, v3, v110
	v_fma_f32 v93, v79, v93, v111
	v_cvt_pk_bf16_f32 v120, v1, v2
	v_cvt_pk_bf16_f32 v121, v3, v93
	global_store_dwordx2 v85, v[120:121], s[98:99] offset:1024
	v_mul_f32_e32 v1, v32, v94
	v_mul_f32_e32 v2, v33, v94
	v_mul_f32_e32 v3, v34, v94
	v_mul_f32_e32 v93, v35, v94
	v_fma_f32 v1, v80, v1, v112
	v_fma_f32 v2, v81, v2, v113
	v_fma_f32 v3, v82, v3, v114
	v_fma_f32 v93, v83, v93, v115
	v_cvt_pk_bf16_f32 v96, v1, v2
	v_cvt_pk_bf16_f32 v97, v3, v93
	global_store_dwordx2 v85, v[96:97], s[98:99] offset:1536
	s_add_i32 s1, s0, 4
	s_min_i32 s1, s1, s11
	s_add_i32 s8, s1, 0xffff0000
	s_cmp_gt_i32 s1, 0xffff
	s_cselect_b32 s1, s8, s1
	s_cselect_b32 s2, s48, s33
	s_cselect_b32 s3, s49, s37
	s_lshl_b32 s8, s1, 12
	s_add_u32 s2, s2, s8
	s_addc_u32 s3, s3, 0
	global_load_dwordx4 v[20:23], v84, s[2:3] nt
	global_load_dwordx4 v[24:27], v84, s[2:3] offset:1024 nt
	global_load_dwordx4 v[28:31], v84, s[2:3] offset:2048 nt
	global_load_dwordx4 v[32:35], v84, s[2:3] offset:3072 nt
	s_add_i32 s0, s0, 1

.LnormQ1_p2_go:
	s_waitcnt vmcnt(20)
	v_mul_f32_e32 v92, v36, v36
	v_fmac_f32_e32 v92, v37, v37
	v_mul_f32_e32 v95, v38, v38
	v_fmac_f32_e32 v95, v39, v39
	v_add_f32_e32 v92, v92, v95
	v_mul_f32_e32 v93, v40, v40
	v_fmac_f32_e32 v93, v41, v41
	v_mul_f32_e32 v95, v42, v42
	v_fmac_f32_e32 v95, v43, v43
	v_add_f32_e32 v93, v93, v95
	v_add_f32_e32 v92, v92, v93
	v_mul_f32_e32 v93, v44, v44
	v_fmac_f32_e32 v93, v45, v45
	v_mul_f32_e32 v95, v46, v46
	v_fmac_f32_e32 v95, v47, v47
	v_add_f32_e32 v93, v93, v95
	v_add_f32_e32 v92, v92, v93
	v_mul_f32_e32 v93, v48, v48
	v_fmac_f32_e32 v93, v49, v49
	v_mul_f32_e32 v95, v50, v50
	v_fmac_f32_e32 v95, v51, v51
	v_add_f32_e32 v93, v93, v95
	v_add_f32_e32 v92, v92, v93
	ds_bpermute_b32 v93, v86, v92
	s_waitcnt lgkmcnt(0)
	v_add_f32_e32 v92, v92, v93
	ds_bpermute_b32 v93, v87, v92
	s_waitcnt lgkmcnt(0)
	v_add_f32_e32 v92, v92, v93
	ds_bpermute_b32 v93, v88, v92
	s_waitcnt lgkmcnt(0)
	v_add_f32_e32 v92, v92, v93
	ds_bpermute_b32 v93, v89, v92
	s_waitcnt lgkmcnt(0)
	v_add_f32_e32 v92, v92, v93
	ds_bpermute_b32 v93, v90, v92
	s_waitcnt lgkmcnt(0)
	v_add_f32_e32 v92, v92, v93
	ds_bpermute_b32 v93, v91, v92
	s_waitcnt lgkmcnt(0)
	v_add_f32_e32 v92, v92, v93
	v_fmamk_f32 v92, v92, 0x3a800000, v206
	v_rsq_f32_e32 v94, v92
	s_lshl_b32 s1, s0, 11
	s_add_u32 s98, s96, s1
	s_addc_u32 s99, s12, 0
	v_mul_f32_e32 v1, v36, v94
	v_mul_f32_e32 v2, v37, v94
	v_mul_f32_e32 v3, v38, v94
	v_mul_f32_e32 v93, v39, v94
	v_fma_f32 v1, v68, v1, v100
	v_fma_f32 v2, v69, v2, v101
	v_fma_f32 v3, v70, v3, v102
	v_fma_f32 v93, v71, v93, v103
	v_cvt_pk_bf16_f32 v116, v1, v2
	v_cvt_pk_bf16_f32 v117, v3, v93
	global_store_dwordx2 v85, v[116:117], s[98:99]
	v_mul_f32_e32 v1, v40, v94
	v_mul_f32_e32 v2, v41, v94
	v_mul_f32_e32 v3, v42, v94
	v_mul_f32_e32 v93, v43, v94
	v_fma_f32 v1, v72, v1, v104
	v_fma_f32 v2, v73, v2, v105
	v_fma_f32 v3, v74, v3, v106
	v_fma_f32 v93, v75, v93, v107
	v_cvt_pk_bf16_f32 v118, v1, v2
	v_cvt_pk_bf16_f32 v119, v3, v93
	global_store_dwordx2 v85, v[118:119], s[98:99] offset:512
	v_mul_f32_e32 v1, v44, v94
	v_mul_f32_e32 v2, v45, v94
	v_mul_f32_e32 v3, v46, v94
	v_mul_f32_e32 v93, v47, v94
	v_fma_f32 v1, v76, v1, v108
	v_fma_f32 v2, v77, v2, v109
	v_fma_f32 v3, v78, v3, v110
	v_fma_f32 v93, v79, v93, v111
	v_cvt_pk_bf16_f32 v120, v1, v2
	v_cvt_pk_bf16_f32 v121, v3, v93
	global_store_dwordx2 v85, v[120:121], s[98:99] offset:1024
	v_mul_f32_e32 v1, v48, v94
	v_mul_f32_e32 v2, v49, v94
	v_mul_f32_e32 v3, v50, v94
	v_mul_f32_e32 v93, v51, v94
	v_fma_f32 v1, v80, v1, v112
	v_fma_f32 v2, v81, v2, v113
	v_fma_f32 v3, v82, v3, v114
	v_fma_f32 v93, v83, v93, v115
	v_cvt_pk_bf16_f32 v96, v1, v2
	v_cvt_pk_bf16_f32 v97, v3, v93
	global_store_dwordx2 v85, v[96:97], s[98:99] offset:1536
	s_add_i32 s1, s0, 4
	s_min_i32 s1, s1, s11
	s_add_i32 s8, s1, 0xffff0000
	s_cmp_gt_i32 s1, 0xffff
	s_cselect_b32 s1, s8, s1
	s_cselect_b32 s2, s48, s33
	s_cselect_b32 s3, s49, s37
	s_lshl_b32 s8, s1, 12
	s_add_u32 s2, s2, s8
	s_addc_u32 s3, s3, 0
	global_load_dwordx4 v[36:39], v84, s[2:3] nt
	global_load_dwordx4 v[40:43], v84, s[2:3] offset:1024 nt
	global_load_dwordx4 v[44:47], v84, s[2:3] offset:2048 nt
	global_load_dwordx4 v[48:51], v84, s[2:3] offset:3072 nt
	s_add_i32 s0, s0, 1

.LnormQ1_p3_go:
	s_waitcnt vmcnt(24)
	v_mul_f32_e32 v92, v52, v52
	v_fmac_f32_e32 v92, v53, v53
	v_mul_f32_e32 v95, v54, v54
	v_fmac_f32_e32 v95, v55, v55
	v_add_f32_e32 v92, v92, v95
	v_mul_f32_e32 v93, v56, v56
	v_fmac_f32_e32 v93, v57, v57
	v_mul_f32_e32 v95, v58, v58
	v_fmac_f32_e32 v95, v59, v59
	v_add_f32_e32 v93, v93, v95
	v_add_f32_e32 v92, v92, v93
	v_mul_f32_e32 v93, v60, v60
	v_fmac_f32_e32 v93, v61, v61
	v_mul_f32_e32 v95, v62, v62
	v_fmac_f32_e32 v95, v63, v63
	v_add_f32_e32 v93, v93, v95
	v_add_f32_e32 v92, v92, v93
	v_mul_f32_e32 v93, v64, v64
	v_fmac_f32_e32 v93, v65, v65
	v_mul_f32_e32 v95, v66, v66
	v_fmac_f32_e32 v95, v67, v67
	v_add_f32_e32 v93, v93, v95
	v_add_f32_e32 v92, v92, v93
	ds_bpermute_b32 v93, v86, v92
	s_waitcnt lgkmcnt(0)
	v_add_f32_e32 v92, v92, v93
	ds_bpermute_b32 v93, v87, v92
	s_waitcnt lgkmcnt(0)
	v_add_f32_e32 v92, v92, v93
	ds_bpermute_b32 v93, v88, v92
	s_waitcnt lgkmcnt(0)
	v_add_f32_e32 v92, v92, v93
	ds_bpermute_b32 v93, v89, v92
	s_waitcnt lgkmcnt(0)
	v_add_f32_e32 v92, v92, v93
	ds_bpermute_b32 v93, v90, v92
	s_waitcnt lgkmcnt(0)
	v_add_f32_e32 v92, v92, v93
	ds_bpermute_b32 v93, v91, v92
	s_waitcnt lgkmcnt(0)
	v_add_f32_e32 v92, v92, v93
	v_fmamk_f32 v92, v92, 0x3a800000, v206
	v_rsq_f32_e32 v94, v92
	s_lshl_b32 s1, s0, 11
	s_add_u32 s98, s96, s1
	s_addc_u32 s99, s12, 0
	v_mul_f32_e32 v1, v52, v94
	v_mul_f32_e32 v2, v53, v94
	v_mul_f32_e32 v3, v54, v94
	v_mul_f32_e32 v93, v55, v94
	v_fma_f32 v1, v68, v1, v100
	v_fma_f32 v2, v69, v2, v101
	v_fma_f32 v3, v70, v3, v102
	v_fma_f32 v93, v71, v93, v103
	v_cvt_pk_bf16_f32 v116, v1, v2
	v_cvt_pk_bf16_f32 v117, v3, v93
	global_store_dwordx2 v85, v[116:117], s[98:99]
	v_mul_f32_e32 v1, v56, v94
	v_mul_f32_e32 v2, v57, v94
	v_mul_f32_e32 v3, v58, v94
	v_mul_f32_e32 v93, v59, v94
	v_fma_f32 v1, v72, v1, v104
	v_fma_f32 v2, v73, v2, v105
	v_fma_f32 v3, v74, v3, v106
	v_fma_f32 v93, v75, v93, v107
	v_cvt_pk_bf16_f32 v118, v1, v2
	v_cvt_pk_bf16_f32 v119, v3, v93
	global_store_dwordx2 v85, v[118:119], s[98:99] offset:512
	v_mul_f32_e32 v1, v60, v94
	v_mul_f32_e32 v2, v61, v94
	v_mul_f32_e32 v3, v62, v94
	v_mul_f32_e32 v93, v63, v94
	v_fma_f32 v1, v76, v1, v108
	v_fma_f32 v2, v77, v2, v109
	v_fma_f32 v3, v78, v3, v110
	v_fma_f32 v93, v79, v93, v111
	v_cvt_pk_bf16_f32 v120, v1, v2
	v_cvt_pk_bf16_f32 v121, v3, v93
	global_store_dwordx2 v85, v[120:121], s[98:99] offset:1024
	v_mul_f32_e32 v1, v64, v94
	v_mul_f32_e32 v2, v65, v94
	v_mul_f32_e32 v3, v66, v94
	v_mul_f32_e32 v93, v67, v94
	v_fma_f32 v1, v80, v1, v112
	v_fma_f32 v2, v81, v2, v113
	v_fma_f32 v3, v82, v3, v114
	v_fma_f32 v93, v83, v93, v115
	v_cvt_pk_bf16_f32 v96, v1, v2
	v_cvt_pk_bf16_f32 v97, v3, v93
	global_store_dwordx2 v85, v[96:97], s[98:99] offset:1536
	s_add_i32 s1, s0, 4
	s_min_i32 s1, s1, s11
	s_add_i32 s8, s1, 0xffff0000
	s_cmp_gt_i32 s1, 0xffff
	s_cselect_b32 s1, s8, s1
	s_cselect_b32 s2, s48, s33
	s_cselect_b32 s3, s49, s37
	s_lshl_b32 s8, s1, 12
	s_add_u32 s2, s2, s8
	s_addc_u32 s3, s3, 0
	global_load_dwordx4 v[52:55], v84, s[2:3] nt
	global_load_dwordx4 v[56:59], v84, s[2:3] offset:1024 nt
	global_load_dwordx4 v[60:63], v84, s[2:3] offset:2048 nt
	global_load_dwordx4 v[64:67], v84, s[2:3] offset:3072 nt
	s_add_i32 s0, s0, 1
.LnormQ1_loop:
.LnormQ1_l0:
	s_cmp_ge_i32 s0, s10
	s_cbranch_scc1 .LnormQ1_done
	s_min_i32 s1, s0, 0x10000
	s_ashr_i32 s1, s1, 13
	s_cmp_eq_u32 s1, s9
	s_cbranch_scc1 .LnormQ1_l0_go
	s_mov_b32 s9, s1
	v_readlane_b32 s2, v255, 7
	v_readlane_b32 s3, v255, 6
	s_add_u32 s2, s2, 0x1000
	s_addc_u32 s3, s3, 0
	s_cmp_lg_u32 s4, 0
	s_cbranch_scc1 .Lq_ng_Q1_l0
	v_readlane_b32 s2, v252, 2
	v_readlane_b32 s3, v252, 3
	s_nop 4

.LnormQ1_l0_go:
	s_waitcnt vmcnt(24)
	v_mul_f32_e32 v92, v4, v4
	v_fmac_f32_e32 v92, v5, v5
	v_mul_f32_e32 v95, v6, v6
	v_fmac_f32_e32 v95, v7, v7
	v_add_f32_e32 v92, v92, v95
	v_mul_f32_e32 v93, v8, v8
	v_fmac_f32_e32 v93, v9, v9
	v_mul_f32_e32 v95, v10, v10
	v_fmac_f32_e32 v95, v11, v11
	v_add_f32_e32 v93, v93, v95
	v_add_f32_e32 v92, v92, v93
	v_mul_f32_e32 v93, v12, v12
	v_fmac_f32_e32 v93, v13, v13
	v_mul_f32_e32 v95, v14, v14
	v_fmac_f32_e32 v95, v15, v15
	v_add_f32_e32 v93, v93, v95
	v_add_f32_e32 v92, v92, v93
	v_mul_f32_e32 v93, v16, v16
	v_fmac_f32_e32 v93, v17, v17
	v_mul_f32_e32 v95, v18, v18
	v_fmac_f32_e32 v95, v19, v19
	v_add_f32_e32 v93, v93, v95
	v_add_f32_e32 v92, v92, v93
	ds_bpermute_b32 v93, v86, v92
	s_waitcnt lgkmcnt(0)
	v_add_f32_e32 v92, v92, v93
	ds_bpermute_b32 v93, v87, v92
	s_waitcnt lgkmcnt(0)
	v_add_f32_e32 v92, v92, v93
	ds_bpermute_b32 v93, v88, v92
	s_waitcnt lgkmcnt(0)
	v_add_f32_e32 v92, v92, v93
	ds_bpermute_b32 v93, v89, v92
	s_waitcnt lgkmcnt(0)
	v_add_f32_e32 v92, v92, v93
	ds_bpermute_b32 v93, v90, v92
	s_waitcnt lgkmcnt(0)
	v_add_f32_e32 v92, v92, v93
	ds_bpermute_b32 v93, v91, v92
	s_waitcnt lgkmcnt(0)
	v_add_f32_e32 v92, v92, v93
	v_fmamk_f32 v92, v92, 0x3a800000, v206
	v_rsq_f32_e32 v94, v92
	s_lshl_b32 s1, s0, 11
	s_add_u32 s98, s96, s1
	s_addc_u32 s99, s12, 0
	v_mul_f32_e32 v1, v4, v94
	v_mul_f32_e32 v2, v5, v94
	v_mul_f32_e32 v3, v6, v94
	v_mul_f32_e32 v93, v7, v94
	v_fma_f32 v1, v68, v1, v100
	v_fma_f32 v2, v69, v2, v101
	v_fma_f32 v3, v70, v3, v102
	v_fma_f32 v93, v71, v93, v103
	v_cvt_pk_bf16_f32 v116, v1, v2
	v_cvt_pk_bf16_f32 v117, v3, v93
	global_store_dwordx2 v85, v[116:117], s[98:99]
	v_mul_f32_e32 v1, v8, v94
	v_mul_f32_e32 v2, v9, v94
	v_mul_f32_e32 v3, v10, v94
	v_mul_f32_e32 v93, v11, v94
	v_fma_f32 v1, v72, v1, v104
	v_fma_f32 v2, v73, v2, v105
	v_fma_f32 v3, v74, v3, v106
	v_fma_f32 v93, v75, v93, v107
	v_cvt_pk_bf16_f32 v118, v1, v2
	v_cvt_pk_bf16_f32 v119, v3, v93
	global_store_dwordx2 v85, v[118:119], s[98:99] offset:512
	v_mul_f32_e32 v1, v12, v94
	v_mul_f32_e32 v2, v13, v94
	v_mul_f32_e32 v3, v14, v94
	v_mul_f32_e32 v93, v15, v94
	v_fma_f32 v1, v76, v1, v108
	v_fma_f32 v2, v77, v2, v109
	v_fma_f32 v3, v78, v3, v110
	v_fma_f32 v93, v79, v93, v111
	v_cvt_pk_bf16_f32 v120, v1, v2
	v_cvt_pk_bf16_f32 v121, v3, v93
	global_store_dwordx2 v85, v[120:121], s[98:99] offset:1024
	v_mul_f32_e32 v1, v16, v94
	v_mul_f32_e32 v2, v17, v94
	v_mul_f32_e32 v3, v18, v94
	v_mul_f32_e32 v93, v19, v94
	v_fma_f32 v1, v80, v1, v112
	v_fma_f32 v2, v81, v2, v113
	v_fma_f32 v3, v82, v3, v114
	v_fma_f32 v93, v83, v93, v115
	v_cvt_pk_bf16_f32 v96, v1, v2
	v_cvt_pk_bf16_f32 v97, v3, v93
	global_store_dwordx2 v85, v[96:97], s[98:99] offset:1536
	s_add_i32 s1, s0, 4
	s_min_i32 s1, s1, s11
	s_add_i32 s8, s1, 0xffff0000
	s_cmp_gt_i32 s1, 0xffff
	s_cselect_b32 s1, s8, s1
	s_cselect_b32 s2, s48, s33
	s_cselect_b32 s3, s49, s37
	s_lshl_b32 s8, s1, 12
	s_add_u32 s2, s2, s8
	s_addc_u32 s3, s3, 0
	global_load_dwordx4 v[4:7], v84, s[2:3] nt
	global_load_dwordx4 v[8:11], v84, s[2:3] offset:1024 nt
	global_load_dwordx4 v[12:15], v84, s[2:3] offset:2048 nt
	global_load_dwordx4 v[16:19], v84, s[2:3] offset:3072 nt
	s_add_i32 s0, s0, 1

.LnormQ1_l1_go:
	s_waitcnt vmcnt(24)
	v_mul_f32_e32 v92, v20, v20
	v_fmac_f32_e32 v92, v21, v21
	v_mul_f32_e32 v95, v22, v22
	v_fmac_f32_e32 v95, v23, v23
	v_add_f32_e32 v92, v92, v95
	v_mul_f32_e32 v93, v24, v24
	v_fmac_f32_e32 v93, v25, v25
	v_mul_f32_e32 v95, v26, v26
	v_fmac_f32_e32 v95, v27, v27
	v_add_f32_e32 v93, v93, v95
	v_add_f32_e32 v92, v92, v93
	v_mul_f32_e32 v93, v28, v28
	v_fmac_f32_e32 v93, v29, v29
	v_mul_f32_e32 v95, v30, v30
	v_fmac_f32_e32 v95, v31, v31
	v_add_f32_e32 v93, v93, v95
	v_add_f32_e32 v92, v92, v93
	v_mul_f32_e32 v93, v32, v32
	v_fmac_f32_e32 v93, v33, v33
	v_mul_f32_e32 v95, v34, v34
	v_fmac_f32_e32 v95, v35, v35
	v_add_f32_e32 v93, v93, v95
	v_add_f32_e32 v92, v92, v93
	ds_bpermute_b32 v93, v86, v92
	s_waitcnt lgkmcnt(0)
	v_add_f32_e32 v92, v92, v93
	ds_bpermute_b32 v93, v87, v92
	s_waitcnt lgkmcnt(0)
	v_add_f32_e32 v92, v92, v93
	ds_bpermute_b32 v93, v88, v92
	s_waitcnt lgkmcnt(0)
	v_add_f32_e32 v92, v92, v93
	ds_bpermute_b32 v93, v89, v92
	s_waitcnt lgkmcnt(0)
	v_add_f32_e32 v92, v92, v93
	ds_bpermute_b32 v93, v90, v92
	s_waitcnt lgkmcnt(0)
	v_add_f32_e32 v92, v92, v93
	ds_bpermute_b32 v93, v91, v92
	s_waitcnt lgkmcnt(0)
	v_add_f32_e32 v92, v92, v93
	v_fmamk_f32 v92, v92, 0x3a800000, v206
	v_rsq_f32_e32 v94, v92
	s_lshl_b32 s1, s0, 11
	s_add_u32 s98, s96, s1
	s_addc_u32 s99, s12, 0
	v_mul_f32_e32 v1, v20, v94
	v_mul_f32_e32 v2, v21, v94
	v_mul_f32_e32 v3, v22, v94
	v_mul_f32_e32 v93, v23, v94
	v_fma_f32 v1, v68, v1, v100
	v_fma_f32 v2, v69, v2, v101
	v_fma_f32 v3, v70, v3, v102
	v_fma_f32 v93, v71, v93, v103
	v_cvt_pk_bf16_f32 v116, v1, v2
	v_cvt_pk_bf16_f32 v117, v3, v93
	global_store_dwordx2 v85, v[116:117], s[98:99]
	v_mul_f32_e32 v1, v24, v94
	v_mul_f32_e32 v2, v25, v94
	v_mul_f32_e32 v3, v26, v94
	v_mul_f32_e32 v93, v27, v94
	v_fma_f32 v1, v72, v1, v104
	v_fma_f32 v2, v73, v2, v105
	v_fma_f32 v3, v74, v3, v106
	v_fma_f32 v93, v75, v93, v107
	v_cvt_pk_bf16_f32 v118, v1, v2
	v_cvt_pk_bf16_f32 v119, v3, v93
	global_store_dwordx2 v85, v[118:119], s[98:99] offset:512
	v_mul_f32_e32 v1, v28, v94
	v_mul_f32_e32 v2, v29, v94
	v_mul_f32_e32 v3, v30, v94
	v_mul_f32_e32 v93, v31, v94
	v_fma_f32 v1, v76, v1, v108
	v_fma_f32 v2, v77, v2, v109
	v_fma_f32 v3, v78, v3, v110
	v_fma_f32 v93, v79, v93, v111
	v_cvt_pk_bf16_f32 v120, v1, v2
	v_cvt_pk_bf16_f32 v121, v3, v93
	global_store_dwordx2 v85, v[120:121], s[98:99] offset:1024
	v_mul_f32_e32 v1, v32, v94
	v_mul_f32_e32 v2, v33, v94
	v_mul_f32_e32 v3, v34, v94
	v_mul_f32_e32 v93, v35, v94
	v_fma_f32 v1, v80, v1, v112
	v_fma_f32 v2, v81, v2, v113
	v_fma_f32 v3, v82, v3, v114
	v_fma_f32 v93, v83, v93, v115
	v_cvt_pk_bf16_f32 v96, v1, v2
	v_cvt_pk_bf16_f32 v97, v3, v93
	global_store_dwordx2 v85, v[96:97], s[98:99] offset:1536
	s_add_i32 s1, s0, 4
	s_min_i32 s1, s1, s11
	s_add_i32 s8, s1, 0xffff0000
	s_cmp_gt_i32 s1, 0xffff
	s_cselect_b32 s1, s8, s1
	s_cselect_b32 s2, s48, s33
	s_cselect_b32 s3, s49, s37
	s_lshl_b32 s8, s1, 12
	s_add_u32 s2, s2, s8
	s_addc_u32 s3, s3, 0
	global_load_dwordx4 v[20:23], v84, s[2:3] nt
	global_load_dwordx4 v[24:27], v84, s[2:3] offset:1024 nt
	global_load_dwordx4 v[28:31], v84, s[2:3] offset:2048 nt
	global_load_dwordx4 v[32:35], v84, s[2:3] offset:3072 nt
	s_add_i32 s0, s0, 1

.LnormQ1_l2_go:
	s_waitcnt vmcnt(24)
	v_mul_f32_e32 v92, v36, v36
	v_fmac_f32_e32 v92, v37, v37
	v_mul_f32_e32 v95, v38, v38
	v_fmac_f32_e32 v95, v39, v39
	v_add_f32_e32 v92, v92, v95
	v_mul_f32_e32 v93, v40, v40
	v_fmac_f32_e32 v93, v41, v41
	v_mul_f32_e32 v95, v42, v42
	v_fmac_f32_e32 v95, v43, v43
	v_add_f32_e32 v93, v93, v95
	v_add_f32_e32 v92, v92, v93
	v_mul_f32_e32 v93, v44, v44
	v_fmac_f32_e32 v93, v45, v45
	v_mul_f32_e32 v95, v46, v46
	v_fmac_f32_e32 v95, v47, v47
	v_add_f32_e32 v93, v93, v95
	v_add_f32_e32 v92, v92, v93
	v_mul_f32_e32 v93, v48, v48
	v_fmac_f32_e32 v93, v49, v49
	v_mul_f32_e32 v95, v50, v50
	v_fmac_f32_e32 v95, v51, v51
	v_add_f32_e32 v93, v93, v95
	v_add_f32_e32 v92, v92, v93
	ds_bpermute_b32 v93, v86, v92
	s_waitcnt lgkmcnt(0)
	v_add_f32_e32 v92, v92, v93
	ds_bpermute_b32 v93, v87, v92
	s_waitcnt lgkmcnt(0)
	v_add_f32_e32 v92, v92, v93
	ds_bpermute_b32 v93, v88, v92
	s_waitcnt lgkmcnt(0)
	v_add_f32_e32 v92, v92, v93
	ds_bpermute_b32 v93, v89, v92
	s_waitcnt lgkmcnt(0)
	v_add_f32_e32 v92, v92, v93
	ds_bpermute_b32 v93, v90, v92
	s_waitcnt lgkmcnt(0)
	v_add_f32_e32 v92, v92, v93
	ds_bpermute_b32 v93, v91, v92
	s_waitcnt lgkmcnt(0)
	v_add_f32_e32 v92, v92, v93
	v_fmamk_f32 v92, v92, 0x3a800000, v206
	v_rsq_f32_e32 v94, v92
	s_lshl_b32 s1, s0, 11
	s_add_u32 s98, s96, s1
	s_addc_u32 s99, s12, 0
	v_mul_f32_e32 v1, v36, v94
	v_mul_f32_e32 v2, v37, v94
	v_mul_f32_e32 v3, v38, v94
	v_mul_f32_e32 v93, v39, v94
	v_fma_f32 v1, v68, v1, v100
	v_fma_f32 v2, v69, v2, v101
	v_fma_f32 v3, v70, v3, v102
	v_fma_f32 v93, v71, v93, v103
	v_cvt_pk_bf16_f32 v116, v1, v2
	v_cvt_pk_bf16_f32 v117, v3, v93
	global_store_dwordx2 v85, v[116:117], s[98:99]
	v_mul_f32_e32 v1, v40, v94
	v_mul_f32_e32 v2, v41, v94
	v_mul_f32_e32 v3, v42, v94
	v_mul_f32_e32 v93, v43, v94
	v_fma_f32 v1, v72, v1, v104
	v_fma_f32 v2, v73, v2, v105
	v_fma_f32 v3, v74, v3, v106
	v_fma_f32 v93, v75, v93, v107
	v_cvt_pk_bf16_f32 v118, v1, v2
	v_cvt_pk_bf16_f32 v119, v3, v93
	global_store_dwordx2 v85, v[118:119], s[98:99] offset:512
	v_mul_f32_e32 v1, v44, v94
	v_mul_f32_e32 v2, v45, v94
	v_mul_f32_e32 v3, v46, v94
	v_mul_f32_e32 v93, v47, v94
	v_fma_f32 v1, v76, v1, v108
	v_fma_f32 v2, v77, v2, v109
	v_fma_f32 v3, v78, v3, v110
	v_fma_f32 v93, v79, v93, v111
	v_cvt_pk_bf16_f32 v120, v1, v2
	v_cvt_pk_bf16_f32 v121, v3, v93
	global_store_dwordx2 v85, v[120:121], s[98:99] offset:1024
	v_mul_f32_e32 v1, v48, v94
	v_mul_f32_e32 v2, v49, v94
	v_mul_f32_e32 v3, v50, v94
	v_mul_f32_e32 v93, v51, v94
	v_fma_f32 v1, v80, v1, v112
	v_fma_f32 v2, v81, v2, v113
	v_fma_f32 v3, v82, v3, v114
	v_fma_f32 v93, v83, v93, v115
	v_cvt_pk_bf16_f32 v96, v1, v2
	v_cvt_pk_bf16_f32 v97, v3, v93
	global_store_dwordx2 v85, v[96:97], s[98:99] offset:1536
	s_add_i32 s1, s0, 4
	s_min_i32 s1, s1, s11
	s_add_i32 s8, s1, 0xffff0000
	s_cmp_gt_i32 s1, 0xffff
	s_cselect_b32 s1, s8, s1
	s_cselect_b32 s2, s48, s33
	s_cselect_b32 s3, s49, s37
	s_lshl_b32 s8, s1, 12
	s_add_u32 s2, s2, s8
	s_addc_u32 s3, s3, 0
	global_load_dwordx4 v[36:39], v84, s[2:3] nt
	global_load_dwordx4 v[40:43], v84, s[2:3] offset:1024 nt
	global_load_dwordx4 v[44:47], v84, s[2:3] offset:2048 nt
	global_load_dwordx4 v[48:51], v84, s[2:3] offset:3072 nt
	s_add_i32 s0, s0, 1

.LnormQ1_l3_go:
	s_waitcnt vmcnt(24)
	v_mul_f32_e32 v92, v52, v52
	v_fmac_f32_e32 v92, v53, v53
	v_mul_f32_e32 v95, v54, v54
	v_fmac_f32_e32 v95, v55, v55
	v_add_f32_e32 v92, v92, v95
	v_mul_f32_e32 v93, v56, v56
	v_fmac_f32_e32 v93, v57, v57
	v_mul_f32_e32 v95, v58, v58
	v_fmac_f32_e32 v95, v59, v59
	v_add_f32_e32 v93, v93, v95
	v_add_f32_e32 v92, v92, v93
	v_mul_f32_e32 v93, v60, v60
	v_fmac_f32_e32 v93, v61, v61
	v_mul_f32_e32 v95, v62, v62
	v_fmac_f32_e32 v95, v63, v63
	v_add_f32_e32 v93, v93, v95
	v_add_f32_e32 v92, v92, v93
	v_mul_f32_e32 v93, v64, v64
	v_fmac_f32_e32 v93, v65, v65
	v_mul_f32_e32 v95, v66, v66
	v_fmac_f32_e32 v95, v67, v67
	v_add_f32_e32 v93, v93, v95
	v_add_f32_e32 v92, v92, v93
	ds_bpermute_b32 v93, v86, v92
	s_waitcnt lgkmcnt(0)
	v_add_f32_e32 v92, v92, v93
	ds_bpermute_b32 v93, v87, v92
	s_waitcnt lgkmcnt(0)
	v_add_f32_e32 v92, v92, v93
	ds_bpermute_b32 v93, v88, v92
	s_waitcnt lgkmcnt(0)
	v_add_f32_e32 v92, v92, v93
	ds_bpermute_b32 v93, v89, v92
	s_waitcnt lgkmcnt(0)
	v_add_f32_e32 v92, v92, v93
	ds_bpermute_b32 v93, v90, v92
	s_waitcnt lgkmcnt(0)
	v_add_f32_e32 v92, v92, v93
	ds_bpermute_b32 v93, v91, v92
	s_waitcnt lgkmcnt(0)
	v_add_f32_e32 v92, v92, v93
	v_fmamk_f32 v92, v92, 0x3a800000, v206
	v_rsq_f32_e32 v94, v92
	s_lshl_b32 s1, s0, 11
	s_add_u32 s98, s96, s1
	s_addc_u32 s99, s12, 0
	v_mul_f32_e32 v1, v52, v94
	v_mul_f32_e32 v2, v53, v94
	v_mul_f32_e32 v3, v54, v94
	v_mul_f32_e32 v93, v55, v94
	v_fma_f32 v1, v68, v1, v100
	v_fma_f32 v2, v69, v2, v101
	v_fma_f32 v3, v70, v3, v102
	v_fma_f32 v93, v71, v93, v103
	v_cvt_pk_bf16_f32 v116, v1, v2
	v_cvt_pk_bf16_f32 v117, v3, v93
	global_store_dwordx2 v85, v[116:117], s[98:99]
	v_mul_f32_e32 v1, v56, v94
	v_mul_f32_e32 v2, v57, v94
	v_mul_f32_e32 v3, v58, v94
	v_mul_f32_e32 v93, v59, v94
	v_fma_f32 v1, v72, v1, v104
	v_fma_f32 v2, v73, v2, v105
	v_fma_f32 v3, v74, v3, v106
	v_fma_f32 v93, v75, v93, v107
	v_cvt_pk_bf16_f32 v118, v1, v2
	v_cvt_pk_bf16_f32 v119, v3, v93
	global_store_dwordx2 v85, v[118:119], s[98:99] offset:512
	v_mul_f32_e32 v1, v60, v94
	v_mul_f32_e32 v2, v61, v94
	v_mul_f32_e32 v3, v62, v94
	v_mul_f32_e32 v93, v63, v94
	v_fma_f32 v1, v76, v1, v108
	v_fma_f32 v2, v77, v2, v109
	v_fma_f32 v3, v78, v3, v110
	v_fma_f32 v93, v79, v93, v111
	v_cvt_pk_bf16_f32 v120, v1, v2
	v_cvt_pk_bf16_f32 v121, v3, v93
	global_store_dwordx2 v85, v[120:121], s[98:99] offset:1024
	v_mul_f32_e32 v1, v64, v94
	v_mul_f32_e32 v2, v65, v94
	v_mul_f32_e32 v3, v66, v94
	v_mul_f32_e32 v93, v67, v94
	v_fma_f32 v1, v80, v1, v112
	v_fma_f32 v2, v81, v2, v113
	v_fma_f32 v3, v82, v3, v114
	v_fma_f32 v93, v83, v93, v115
	v_cvt_pk_bf16_f32 v96, v1, v2
	v_cvt_pk_bf16_f32 v97, v3, v93
	global_store_dwordx2 v85, v[96:97], s[98:99] offset:1536
	s_add_i32 s1, s0, 4
	s_min_i32 s1, s1, s11
	s_add_i32 s8, s1, 0xffff0000
	s_cmp_gt_i32 s1, 0xffff
	s_cselect_b32 s1, s8, s1
	s_cselect_b32 s2, s48, s33
	s_cselect_b32 s3, s49, s37
	s_lshl_b32 s8, s1, 12
	s_add_u32 s2, s2, s8
	s_addc_u32 s3, s3, 0
	global_load_dwordx4 v[52:55], v84, s[2:3] nt
	global_load_dwordx4 v[56:59], v84, s[2:3] offset:1024 nt
	global_load_dwordx4 v[60:63], v84, s[2:3] offset:2048 nt
	global_load_dwordx4 v[64:67], v84, s[2:3] offset:3072 nt
	s_add_i32 s0, s0, 1
	s_branch .LnormQ1_loop
.LnormQ1_done:
	s_waitcnt vmcnt(0)
	s_mov_b64 s[22:23], 0x1000
.Lq_idle_out:
	s_branch .LBB0_367
.LBB0_366:
	s_waitcnt vmcnt(0)
	v_readlane_b32 s90, v254, 57
	v_readlane_b32 s56, v254, 59
	v_readlane_b32 s52, v254, 61
	v_readlane_b32 s91, v254, 58
	v_readlane_b32 s57, v254, 60
	v_readlane_b32 s53, v254, 62
	s_mov_b32 s92, 0x80000
	s_mov_b32 s93, 0x90000
	s_mov_b32 s88, 0xa0000
	s_mov_b32 s89, 0xb0000
	s_mov_b64 s[22:23], 0x1000
	s_mov_b64 s[66:67], 0x800
	s_barrier

.LBB0_419:
	s_or_b64 exec, exec, s[0:1]
	s_andn2_b64 vcc, exec, s[4:5]
	s_mov_b64 s[0:1], -1
	s_waitcnt lgkmcnt(0)
	s_barrier
	v_mov_b32_e32 v4, 0x20180
	ds_read_b32 v5, v4
	s_waitcnt lgkmcnt(0)
	s_barrier
	v_readfirstlane_b32 s98, v5
	s_cmp_eq_u32 s98, 1
	s_cbranch_scc1 .Lq_to_pass2
	s_cmp_eq_u32 s98, 2
	s_cbranch_scc0 .Lq_done
	v_mov_b32_e32 v5, 0
	ds_write_b32 v4, v5
	s_mov_b32 s98, s48
	s_mov_b32 s48, s33
	s_mov_b32 s33, s98
	s_mov_b32 s98, s49
	s_mov_b32 s49, s37
	s_mov_b32 s37, s98
	s_sub_u32 s34, s34, 0x16000000
	s_subb_u32 s35, s35, 0
	s_movk_i32 s71, 0x108
	v_mov_b32_e32 v5, 1
	ds_write_b32 v4, v5 offset:4
	v_readfirstlane_b32 s0, v207
	s_ashr_i32 s0, s0, 6
	s_lshl_b32 s1, s24, 3
	s_add_i32 s0, s0, s1
	s_add_i32 s0, s0, 0x10000
	s_add_i32 s10, s0, 1
	v_readlane_b32 s12, v252, 53
	v_and_b32_e32 v1, 63, v207
	v_lshlrev_b32_e32 v84, 4, v1
	v_lshlrev_b32_e32 v85, 3, v1
	v_xor_b32_e32 v86, 1, v1
	v_lshlrev_b32_e32 v86, 2, v86
	v_xor_b32_e32 v87, 2, v1
	v_lshlrev_b32_e32 v87, 2, v87
	v_xor_b32_e32 v88, 4, v1
	v_lshlrev_b32_e32 v88, 2, v88
	v_xor_b32_e32 v89, 8, v1
	v_lshlrev_b32_e32 v89, 2, v89
	v_xor_b32_e32 v90, 16, v1
	v_lshlrev_b32_e32 v90, 2, v90
	v_xor_b32_e32 v91, 32, v1
	v_lshlrev_b32_e32 v91, 2, v91
	s_add_i32 s11, s10, -1
	s_mov_b32 s9, -1
	s_add_i32 s1, s0, 0
	s_min_i32 s1, s1, s11
	s_add_i32 s8, s1, 0xffff0000
	s_cmp_gt_i32 s1, 0xffff
	s_cselect_b32 s1, s8, s1
	s_cselect_b32 s2, s33, s48
	s_cselect_b32 s3, s37, s49
	s_lshl_b32 s8, s1, 12
	s_add_u32 s2, s2, s8
	s_addc_u32 s3, s3, 0
	global_load_dwordx4 v[4:7], v84, s[2:3] nt
	global_load_dwordx4 v[8:11], v84, s[2:3] offset:1024 nt
	global_load_dwordx4 v[12:15], v84, s[2:3] offset:2048 nt
	global_load_dwordx4 v[16:19], v84, s[2:3] offset:3072 nt
	s_add_i32 s1, s0, 1
	s_min_i32 s1, s1, s11
	s_add_i32 s8, s1, 0xffff0000
	s_cmp_gt_i32 s1, 0xffff
	s_cselect_b32 s1, s8, s1
	s_cselect_b32 s2, s33, s48
	s_cselect_b32 s3, s37, s49
	s_lshl_b32 s8, s1, 12
	s_add_u32 s2, s2, s8
	s_addc_u32 s3, s3, 0
	global_load_dwordx4 v[20:23], v84, s[2:3] nt
	global_load_dwordx4 v[24:27], v84, s[2:3] offset:1024 nt
	global_load_dwordx4 v[28:31], v84, s[2:3] offset:2048 nt
	global_load_dwordx4 v[32:35], v84, s[2:3] offset:3072 nt
	s_add_i32 s1, s0, 2
	s_min_i32 s1, s1, s11
	s_add_i32 s8, s1, 0xffff0000
	s_cmp_gt_i32 s1, 0xffff
	s_cselect_b32 s1, s8, s1
	s_cselect_b32 s2, s33, s48
	s_cselect_b32 s3, s37, s49
	s_lshl_b32 s8, s1, 12
	s_add_u32 s2, s2, s8
	s_addc_u32 s3, s3, 0
	global_load_dwordx4 v[36:39], v84, s[2:3] nt
	global_load_dwordx4 v[40:43], v84, s[2:3] offset:1024 nt
	global_load_dwordx4 v[44:47], v84, s[2:3] offset:2048 nt
	global_load_dwordx4 v[48:51], v84, s[2:3] offset:3072 nt
	s_add_i32 s1, s0, 3
	s_min_i32 s1, s1, s11
	s_add_i32 s8, s1, 0xffff0000
	s_cmp_gt_i32 s1, 0xffff
	s_cselect_b32 s1, s8, s1
	s_cselect_b32 s2, s33, s48
	s_cselect_b32 s3, s37, s49
	s_lshl_b32 s8, s1, 12
	s_add_u32 s2, s2, s8
	s_addc_u32 s3, s3, 0
	global_load_dwordx4 v[52:55], v84, s[2:3] nt
	global_load_dwordx4 v[56:59], v84, s[2:3] offset:1024 nt
	global_load_dwordx4 v[60:63], v84, s[2:3] offset:2048 nt
	global_load_dwordx4 v[64:67], v84, s[2:3] offset:3072 nt

.LnormQ2_p0_go:
	s_waitcnt vmcnt(12)
	v_mul_f32_e32 v92, v4, v4
	v_fmac_f32_e32 v92, v5, v5
	v_mul_f32_e32 v95, v6, v6
	v_fmac_f32_e32 v95, v7, v7
	v_add_f32_e32 v92, v92, v95
	v_mul_f32_e32 v93, v8, v8
	v_fmac_f32_e32 v93, v9, v9
	v_mul_f32_e32 v95, v10, v10
	v_fmac_f32_e32 v95, v11, v11
	v_add_f32_e32 v93, v93, v95
	v_add_f32_e32 v92, v92, v93
	v_mul_f32_e32 v93, v12, v12
	v_fmac_f32_e32 v93, v13, v13
	v_mul_f32_e32 v95, v14, v14
	v_fmac_f32_e32 v95, v15, v15
	v_add_f32_e32 v93, v93, v95
	v_add_f32_e32 v92, v92, v93
	v_mul_f32_e32 v93, v16, v16
	v_fmac_f32_e32 v93, v17, v17
	v_mul_f32_e32 v95, v18, v18
	v_fmac_f32_e32 v95, v19, v19
	v_add_f32_e32 v93, v93, v95
	v_add_f32_e32 v92, v92, v93
	ds_bpermute_b32 v93, v86, v92
	s_waitcnt lgkmcnt(0)
	v_add_f32_e32 v92, v92, v93
	ds_bpermute_b32 v93, v87, v92
	s_waitcnt lgkmcnt(0)
	v_add_f32_e32 v92, v92, v93
	ds_bpermute_b32 v93, v88, v92
	s_waitcnt lgkmcnt(0)
	v_add_f32_e32 v92, v92, v93
	ds_bpermute_b32 v93, v89, v92
	s_waitcnt lgkmcnt(0)
	v_add_f32_e32 v92, v92, v93
	ds_bpermute_b32 v93, v90, v92
	s_waitcnt lgkmcnt(0)
	v_add_f32_e32 v92, v92, v93
	ds_bpermute_b32 v93, v91, v92
	s_waitcnt lgkmcnt(0)
	v_add_f32_e32 v92, v92, v93
	v_fmamk_f32 v92, v92, 0x3a800000, v206
	v_rsq_f32_e32 v94, v92
	s_lshl_b32 s1, s0, 11
	s_add_u32 s98, s96, s1
	s_addc_u32 s99, s12, 0
	v_mul_f32_e32 v1, v4, v94
	v_mul_f32_e32 v2, v5, v94
	v_mul_f32_e32 v3, v6, v94
	v_mul_f32_e32 v93, v7, v94
	v_fma_f32 v1, v68, v1, v100
	v_fma_f32 v2, v69, v2, v101
	v_fma_f32 v3, v70, v3, v102
	v_fma_f32 v93, v71, v93, v103
	v_cvt_pk_bf16_f32 v116, v1, v2
	v_cvt_pk_bf16_f32 v117, v3, v93
	global_store_dwordx2 v85, v[116:117], s[98:99]
	v_mul_f32_e32 v1, v8, v94
	v_mul_f32_e32 v2, v9, v94
	v_mul_f32_e32 v3, v10, v94
	v_mul_f32_e32 v93, v11, v94
	v_fma_f32 v1, v72, v1, v104
	v_fma_f32 v2, v73, v2, v105
	v_fma_f32 v3, v74, v3, v106
	v_fma_f32 v93, v75, v93, v107
	v_cvt_pk_bf16_f32 v118, v1, v2
	v_cvt_pk_bf16_f32 v119, v3, v93
	global_store_dwordx2 v85, v[118:119], s[98:99] offset:512
	v_mul_f32_e32 v1, v12, v94
	v_mul_f32_e32 v2, v13, v94
	v_mul_f32_e32 v3, v14, v94
	v_mul_f32_e32 v93, v15, v94
	v_fma_f32 v1, v76, v1, v108
	v_fma_f32 v2, v77, v2, v109
	v_fma_f32 v3, v78, v3, v110
	v_fma_f32 v93, v79, v93, v111
	v_cvt_pk_bf16_f32 v120, v1, v2
	v_cvt_pk_bf16_f32 v121, v3, v93
	global_store_dwordx2 v85, v[120:121], s[98:99] offset:1024
	v_mul_f32_e32 v1, v16, v94
	v_mul_f32_e32 v2, v17, v94
	v_mul_f32_e32 v3, v18, v94
	v_mul_f32_e32 v93, v19, v94
	v_fma_f32 v1, v80, v1, v112
	v_fma_f32 v2, v81, v2, v113
	v_fma_f32 v3, v82, v3, v114
	v_fma_f32 v93, v83, v93, v115
	v_cvt_pk_bf16_f32 v96, v1, v2
	v_cvt_pk_bf16_f32 v97, v3, v93
	global_store_dwordx2 v85, v[96:97], s[98:99] offset:1536
	s_add_i32 s1, s0, 4
	s_min_i32 s1, s1, s11
	s_add_i32 s8, s1, 0xffff0000
	s_cmp_gt_i32 s1, 0xffff
	s_cselect_b32 s1, s8, s1
	s_cselect_b32 s2, s33, s48
	s_cselect_b32 s3, s37, s49
	s_lshl_b32 s8, s1, 12
	s_add_u32 s2, s2, s8
	s_addc_u32 s3, s3, 0
	global_load_dwordx4 v[4:7], v84, s[2:3] nt
	global_load_dwordx4 v[8:11], v84, s[2:3] offset:1024 nt
	global_load_dwordx4 v[12:15], v84, s[2:3] offset:2048 nt
	global_load_dwordx4 v[16:19], v84, s[2:3] offset:3072 nt
	s_add_i32 s0, s0, 1

.LnormQ2_p1_go:
	s_waitcnt vmcnt(16)
	v_mul_f32_e32 v92, v20, v20
	v_fmac_f32_e32 v92, v21, v21
	v_mul_f32_e32 v95, v22, v22
	v_fmac_f32_e32 v95, v23, v23
	v_add_f32_e32 v92, v92, v95
	v_mul_f32_e32 v93, v24, v24
	v_fmac_f32_e32 v93, v25, v25
	v_mul_f32_e32 v95, v26, v26
	v_fmac_f32_e32 v95, v27, v27
	v_add_f32_e32 v93, v93, v95
	v_add_f32_e32 v92, v92, v93
	v_mul_f32_e32 v93, v28, v28
	v_fmac_f32_e32 v93, v29, v29
	v_mul_f32_e32 v95, v30, v30
	v_fmac_f32_e32 v95, v31, v31
	v_add_f32_e32 v93, v93, v95
	v_add_f32_e32 v92, v92, v93
	v_mul_f32_e32 v93, v32, v32
	v_fmac_f32_e32 v93, v33, v33
	v_mul_f32_e32 v95, v34, v34
	v_fmac_f32_e32 v95, v35, v35
	v_add_f32_e32 v93, v93, v95
	v_add_f32_e32 v92, v92, v93
	ds_bpermute_b32 v93, v86, v92
	s_waitcnt lgkmcnt(0)
	v_add_f32_e32 v92, v92, v93
	ds_bpermute_b32 v93, v87, v92
	s_waitcnt lgkmcnt(0)
	v_add_f32_e32 v92, v92, v93
	ds_bpermute_b32 v93, v88, v92
	s_waitcnt lgkmcnt(0)
	v_add_f32_e32 v92, v92, v93
	ds_bpermute_b32 v93, v89, v92
	s_waitcnt lgkmcnt(0)
	v_add_f32_e32 v92, v92, v93
	ds_bpermute_b32 v93, v90, v92
	s_waitcnt lgkmcnt(0)
	v_add_f32_e32 v92, v92, v93
	ds_bpermute_b32 v93, v91, v92
	s_waitcnt lgkmcnt(0)
	v_add_f32_e32 v92, v92, v93
	v_fmamk_f32 v92, v92, 0x3a800000, v206
	v_rsq_f32_e32 v94, v92
	s_lshl_b32 s1, s0, 11
	s_add_u32 s98, s96, s1
	s_addc_u32 s99, s12, 0
	v_mul_f32_e32 v1, v20, v94
	v_mul_f32_e32 v2, v21, v94
	v_mul_f32_e32 v3, v22, v94
	v_mul_f32_e32 v93, v23, v94
	v_fma_f32 v1, v68, v1, v100
	v_fma_f32 v2, v69, v2, v101
	v_fma_f32 v3, v70, v3, v102
	v_fma_f32 v93, v71, v93, v103
	v_cvt_pk_bf16_f32 v116, v1, v2
	v_cvt_pk_bf16_f32 v117, v3, v93
	global_store_dwordx2 v85, v[116:117], s[98:99]
	v_mul_f32_e32 v1, v24, v94
	v_mul_f32_e32 v2, v25, v94
	v_mul_f32_e32 v3, v26, v94
	v_mul_f32_e32 v93, v27, v94
	v_fma_f32 v1, v72, v1, v104
	v_fma_f32 v2, v73, v2, v105
	v_fma_f32 v3, v74, v3, v106
	v_fma_f32 v93, v75, v93, v107
	v_cvt_pk_bf16_f32 v118, v1, v2
	v_cvt_pk_bf16_f32 v119, v3, v93
	global_store_dwordx2 v85, v[118:119], s[98:99] offset:512
	v_mul_f32_e32 v1, v28, v94
	v_mul_f32_e32 v2, v29, v94
	v_mul_f32_e32 v3, v30, v94
	v_mul_f32_e32 v93, v31, v94
	v_fma_f32 v1, v76, v1, v108
	v_fma_f32 v2, v77, v2, v109
	v_fma_f32 v3, v78, v3, v110
	v_fma_f32 v93, v79, v93, v111
	v_cvt_pk_bf16_f32 v120, v1, v2
	v_cvt_pk_bf16_f32 v121, v3, v93
	global_store_dwordx2 v85, v[120:121], s[98:99] offset:1024
	v_mul_f32_e32 v1, v32, v94
	v_mul_f32_e32 v2, v33, v94
	v_mul_f32_e32 v3, v34, v94
	v_mul_f32_e32 v93, v35, v94
	v_fma_f32 v1, v80, v1, v112
	v_fma_f32 v2, v81, v2, v113
	v_fma_f32 v3, v82, v3, v114
	v_fma_f32 v93, v83, v93, v115
	v_cvt_pk_bf16_f32 v96, v1, v2
	v_cvt_pk_bf16_f32 v97, v3, v93
	global_store_dwordx2 v85, v[96:97], s[98:99] offset:1536
	s_add_i32 s1, s0, 4
	s_min_i32 s1, s1, s11
	s_add_i32 s8, s1, 0xffff0000
	s_cmp_gt_i32 s1, 0xffff
	s_cselect_b32 s1, s8, s1
	s_cselect_b32 s2, s33, s48
	s_cselect_b32 s3, s37, s49
	s_lshl_b32 s8, s1, 12
	s_add_u32 s2, s2, s8
	s_addc_u32 s3, s3, 0
	global_load_dwordx4 v[20:23], v84, s[2:3] nt
	global_load_dwordx4 v[24:27], v84, s[2:3] offset:1024 nt
	global_load_dwordx4 v[28:31], v84, s[2:3] offset:2048 nt
	global_load_dwordx4 v[32:35], v84, s[2:3] offset:3072 nt
	s_add_i32 s0, s0, 1

.LnormQ2_p2_go:
	s_waitcnt vmcnt(20)
	v_mul_f32_e32 v92, v36, v36
	v_fmac_f32_e32 v92, v37, v37
	v_mul_f32_e32 v95, v38, v38
	v_fmac_f32_e32 v95, v39, v39
	v_add_f32_e32 v92, v92, v95
	v_mul_f32_e32 v93, v40, v40
	v_fmac_f32_e32 v93, v41, v41
	v_mul_f32_e32 v95, v42, v42
	v_fmac_f32_e32 v95, v43, v43
	v_add_f32_e32 v93, v93, v95
	v_add_f32_e32 v92, v92, v93
	v_mul_f32_e32 v93, v44, v44
	v_fmac_f32_e32 v93, v45, v45
	v_mul_f32_e32 v95, v46, v46
	v_fmac_f32_e32 v95, v47, v47
	v_add_f32_e32 v93, v93, v95
	v_add_f32_e32 v92, v92, v93
	v_mul_f32_e32 v93, v48, v48
	v_fmac_f32_e32 v93, v49, v49
	v_mul_f32_e32 v95, v50, v50
	v_fmac_f32_e32 v95, v51, v51
	v_add_f32_e32 v93, v93, v95
	v_add_f32_e32 v92, v92, v93
	ds_bpermute_b32 v93, v86, v92
	s_waitcnt lgkmcnt(0)
	v_add_f32_e32 v92, v92, v93
	ds_bpermute_b32 v93, v87, v92
	s_waitcnt lgkmcnt(0)
	v_add_f32_e32 v92, v92, v93
	ds_bpermute_b32 v93, v88, v92
	s_waitcnt lgkmcnt(0)
	v_add_f32_e32 v92, v92, v93
	ds_bpermute_b32 v93, v89, v92
	s_waitcnt lgkmcnt(0)
	v_add_f32_e32 v92, v92, v93
	ds_bpermute_b32 v93, v90, v92
	s_waitcnt lgkmcnt(0)
	v_add_f32_e32 v92, v92, v93
	ds_bpermute_b32 v93, v91, v92
	s_waitcnt lgkmcnt(0)
	v_add_f32_e32 v92, v92, v93
	v_fmamk_f32 v92, v92, 0x3a800000, v206
	v_rsq_f32_e32 v94, v92
	s_lshl_b32 s1, s0, 11
	s_add_u32 s98, s96, s1
	s_addc_u32 s99, s12, 0
	v_mul_f32_e32 v1, v36, v94
	v_mul_f32_e32 v2, v37, v94
	v_mul_f32_e32 v3, v38, v94
	v_mul_f32_e32 v93, v39, v94
	v_fma_f32 v1, v68, v1, v100
	v_fma_f32 v2, v69, v2, v101
	v_fma_f32 v3, v70, v3, v102
	v_fma_f32 v93, v71, v93, v103
	v_cvt_pk_bf16_f32 v116, v1, v2
	v_cvt_pk_bf16_f32 v117, v3, v93
	global_store_dwordx2 v85, v[116:117], s[98:99]
	v_mul_f32_e32 v1, v40, v94
	v_mul_f32_e32 v2, v41, v94
	v_mul_f32_e32 v3, v42, v94
	v_mul_f32_e32 v93, v43, v94
	v_fma_f32 v1, v72, v1, v104
	v_fma_f32 v2, v73, v2, v105
	v_fma_f32 v3, v74, v3, v106
	v_fma_f32 v93, v75, v93, v107
	v_cvt_pk_bf16_f32 v118, v1, v2
	v_cvt_pk_bf16_f32 v119, v3, v93
	global_store_dwordx2 v85, v[118:119], s[98:99] offset:512
	v_mul_f32_e32 v1, v44, v94
	v_mul_f32_e32 v2, v45, v94
	v_mul_f32_e32 v3, v46, v94
	v_mul_f32_e32 v93, v47, v94
	v_fma_f32 v1, v76, v1, v108
	v_fma_f32 v2, v77, v2, v109
	v_fma_f32 v3, v78, v3, v110
	v_fma_f32 v93, v79, v93, v111
	v_cvt_pk_bf16_f32 v120, v1, v2
	v_cvt_pk_bf16_f32 v121, v3, v93
	global_store_dwordx2 v85, v[120:121], s[98:99] offset:1024
	v_mul_f32_e32 v1, v48, v94
	v_mul_f32_e32 v2, v49, v94
	v_mul_f32_e32 v3, v50, v94
	v_mul_f32_e32 v93, v51, v94
	v_fma_f32 v1, v80, v1, v112
	v_fma_f32 v2, v81, v2, v113
	v_fma_f32 v3, v82, v3, v114
	v_fma_f32 v93, v83, v93, v115
	v_cvt_pk_bf16_f32 v96, v1, v2
	v_cvt_pk_bf16_f32 v97, v3, v93
	global_store_dwordx2 v85, v[96:97], s[98:99] offset:1536
	s_add_i32 s1, s0, 4
	s_min_i32 s1, s1, s11
	s_add_i32 s8, s1, 0xffff0000
	s_cmp_gt_i32 s1, 0xffff
	s_cselect_b32 s1, s8, s1
	s_cselect_b32 s2, s33, s48
	s_cselect_b32 s3, s37, s49
	s_lshl_b32 s8, s1, 12
	s_add_u32 s2, s2, s8
	s_addc_u32 s3, s3, 0
	global_load_dwordx4 v[36:39], v84, s[2:3] nt
	global_load_dwordx4 v[40:43], v84, s[2:3] offset:1024 nt
	global_load_dwordx4 v[44:47], v84, s[2:3] offset:2048 nt
	global_load_dwordx4 v[48:51], v84, s[2:3] offset:3072 nt
	s_add_i32 s0, s0, 1

.LnormQ2_p3_go:
	s_waitcnt vmcnt(24)
	v_mul_f32_e32 v92, v52, v52
	v_fmac_f32_e32 v92, v53, v53
	v_mul_f32_e32 v95, v54, v54
	v_fmac_f32_e32 v95, v55, v55
	v_add_f32_e32 v92, v92, v95
	v_mul_f32_e32 v93, v56, v56
	v_fmac_f32_e32 v93, v57, v57
	v_mul_f32_e32 v95, v58, v58
	v_fmac_f32_e32 v95, v59, v59
	v_add_f32_e32 v93, v93, v95
	v_add_f32_e32 v92, v92, v93
	v_mul_f32_e32 v93, v60, v60
	v_fmac_f32_e32 v93, v61, v61
	v_mul_f32_e32 v95, v62, v62
	v_fmac_f32_e32 v95, v63, v63
	v_add_f32_e32 v93, v93, v95
	v_add_f32_e32 v92, v92, v93
	v_mul_f32_e32 v93, v64, v64
	v_fmac_f32_e32 v93, v65, v65
	v_mul_f32_e32 v95, v66, v66
	v_fmac_f32_e32 v95, v67, v67
	v_add_f32_e32 v93, v93, v95
	v_add_f32_e32 v92, v92, v93
	ds_bpermute_b32 v93, v86, v92
	s_waitcnt lgkmcnt(0)
	v_add_f32_e32 v92, v92, v93
	ds_bpermute_b32 v93, v87, v92
	s_waitcnt lgkmcnt(0)
	v_add_f32_e32 v92, v92, v93
	ds_bpermute_b32 v93, v88, v92
	s_waitcnt lgkmcnt(0)
	v_add_f32_e32 v92, v92, v93
	ds_bpermute_b32 v93, v89, v92
	s_waitcnt lgkmcnt(0)
	v_add_f32_e32 v92, v92, v93
	ds_bpermute_b32 v93, v90, v92
	s_waitcnt lgkmcnt(0)
	v_add_f32_e32 v92, v92, v93
	ds_bpermute_b32 v93, v91, v92
	s_waitcnt lgkmcnt(0)
	v_add_f32_e32 v92, v92, v93
	v_fmamk_f32 v92, v92, 0x3a800000, v206
	v_rsq_f32_e32 v94, v92
	s_lshl_b32 s1, s0, 11
	s_add_u32 s98, s96, s1
	s_addc_u32 s99, s12, 0
	v_mul_f32_e32 v1, v52, v94
	v_mul_f32_e32 v2, v53, v94
	v_mul_f32_e32 v3, v54, v94
	v_mul_f32_e32 v93, v55, v94
	v_fma_f32 v1, v68, v1, v100
	v_fma_f32 v2, v69, v2, v101
	v_fma_f32 v3, v70, v3, v102
	v_fma_f32 v93, v71, v93, v103
	v_cvt_pk_bf16_f32 v116, v1, v2
	v_cvt_pk_bf16_f32 v117, v3, v93
	global_store_dwordx2 v85, v[116:117], s[98:99]
	v_mul_f32_e32 v1, v56, v94
	v_mul_f32_e32 v2, v57, v94
	v_mul_f32_e32 v3, v58, v94
	v_mul_f32_e32 v93, v59, v94
	v_fma_f32 v1, v72, v1, v104
	v_fma_f32 v2, v73, v2, v105
	v_fma_f32 v3, v74, v3, v106
	v_fma_f32 v93, v75, v93, v107
	v_cvt_pk_bf16_f32 v118, v1, v2
	v_cvt_pk_bf16_f32 v119, v3, v93
	global_store_dwordx2 v85, v[118:119], s[98:99] offset:512
	v_mul_f32_e32 v1, v60, v94
	v_mul_f32_e32 v2, v61, v94
	v_mul_f32_e32 v3, v62, v94
	v_mul_f32_e32 v93, v63, v94
	v_fma_f32 v1, v76, v1, v108
	v_fma_f32 v2, v77, v2, v109
	v_fma_f32 v3, v78, v3, v110
	v_fma_f32 v93, v79, v93, v111
	v_cvt_pk_bf16_f32 v120, v1, v2
	v_cvt_pk_bf16_f32 v121, v3, v93
	global_store_dwordx2 v85, v[120:121], s[98:99] offset:1024
	v_mul_f32_e32 v1, v64, v94
	v_mul_f32_e32 v2, v65, v94
	v_mul_f32_e32 v3, v66, v94
	v_mul_f32_e32 v93, v67, v94
	v_fma_f32 v1, v80, v1, v112
	v_fma_f32 v2, v81, v2, v113
	v_fma_f32 v3, v82, v3, v114
	v_fma_f32 v93, v83, v93, v115
	v_cvt_pk_bf16_f32 v96, v1, v2
	v_cvt_pk_bf16_f32 v97, v3, v93
	global_store_dwordx2 v85, v[96:97], s[98:99] offset:1536
	s_add_i32 s1, s0, 4
	s_min_i32 s1, s1, s11
	s_add_i32 s8, s1, 0xffff0000
	s_cmp_gt_i32 s1, 0xffff
	s_cselect_b32 s1, s8, s1
	s_cselect_b32 s2, s33, s48
	s_cselect_b32 s3, s37, s49
	s_lshl_b32 s8, s1, 12
	s_add_u32 s2, s2, s8
	s_addc_u32 s3, s3, 0
	global_load_dwordx4 v[52:55], v84, s[2:3] nt
	global_load_dwordx4 v[56:59], v84, s[2:3] offset:1024 nt
	global_load_dwordx4 v[60:63], v84, s[2:3] offset:2048 nt
	global_load_dwordx4 v[64:67], v84, s[2:3] offset:3072 nt
	s_add_i32 s0, s0, 1

.LnormQ2_l0_go:
	s_waitcnt vmcnt(24)
	v_mul_f32_e32 v92, v4, v4
	v_fmac_f32_e32 v92, v5, v5
	v_mul_f32_e32 v95, v6, v6
	v_fmac_f32_e32 v95, v7, v7
	v_add_f32_e32 v92, v92, v95
	v_mul_f32_e32 v93, v8, v8
	v_fmac_f32_e32 v93, v9, v9
	v_mul_f32_e32 v95, v10, v10
	v_fmac_f32_e32 v95, v11, v11
	v_add_f32_e32 v93, v93, v95
	v_add_f32_e32 v92, v92, v93
	v_mul_f32_e32 v93, v12, v12
	v_fmac_f32_e32 v93, v13, v13
	v_mul_f32_e32 v95, v14, v14
	v_fmac_f32_e32 v95, v15, v15
	v_add_f32_e32 v93, v93, v95
	v_add_f32_e32 v92, v92, v93
	v_mul_f32_e32 v93, v16, v16
	v_fmac_f32_e32 v93, v17, v17
	v_mul_f32_e32 v95, v18, v18
	v_fmac_f32_e32 v95, v19, v19
	v_add_f32_e32 v93, v93, v95
	v_add_f32_e32 v92, v92, v93
	ds_bpermute_b32 v93, v86, v92
	s_waitcnt lgkmcnt(0)
	v_add_f32_e32 v92, v92, v93
	ds_bpermute_b32 v93, v87, v92
	s_waitcnt lgkmcnt(0)
	v_add_f32_e32 v92, v92, v93
	ds_bpermute_b32 v93, v88, v92
	s_waitcnt lgkmcnt(0)
	v_add_f32_e32 v92, v92, v93
	ds_bpermute_b32 v93, v89, v92
	s_waitcnt lgkmcnt(0)
	v_add_f32_e32 v92, v92, v93
	ds_bpermute_b32 v93, v90, v92
	s_waitcnt lgkmcnt(0)
	v_add_f32_e32 v92, v92, v93
	ds_bpermute_b32 v93, v91, v92
	s_waitcnt lgkmcnt(0)
	v_add_f32_e32 v92, v92, v93
	v_fmamk_f32 v92, v92, 0x3a800000, v206
	v_rsq_f32_e32 v94, v92
	s_lshl_b32 s1, s0, 11
	s_add_u32 s98, s96, s1
	s_addc_u32 s99, s12, 0
	v_mul_f32_e32 v1, v4, v94
	v_mul_f32_e32 v2, v5, v94
	v_mul_f32_e32 v3, v6, v94
	v_mul_f32_e32 v93, v7, v94
	v_fma_f32 v1, v68, v1, v100
	v_fma_f32 v2, v69, v2, v101
	v_fma_f32 v3, v70, v3, v102
	v_fma_f32 v93, v71, v93, v103
	v_cvt_pk_bf16_f32 v116, v1, v2
	v_cvt_pk_bf16_f32 v117, v3, v93
	global_store_dwordx2 v85, v[116:117], s[98:99]
	v_mul_f32_e32 v1, v8, v94
	v_mul_f32_e32 v2, v9, v94
	v_mul_f32_e32 v3, v10, v94
	v_mul_f32_e32 v93, v11, v94
	v_fma_f32 v1, v72, v1, v104
	v_fma_f32 v2, v73, v2, v105
	v_fma_f32 v3, v74, v3, v106
	v_fma_f32 v93, v75, v93, v107
	v_cvt_pk_bf16_f32 v118, v1, v2
	v_cvt_pk_bf16_f32 v119, v3, v93
	global_store_dwordx2 v85, v[118:119], s[98:99] offset:512
	v_mul_f32_e32 v1, v12, v94
	v_mul_f32_e32 v2, v13, v94
	v_mul_f32_e32 v3, v14, v94
	v_mul_f32_e32 v93, v15, v94
	v_fma_f32 v1, v76, v1, v108
	v_fma_f32 v2, v77, v2, v109
	v_fma_f32 v3, v78, v3, v110
	v_fma_f32 v93, v79, v93, v111
	v_cvt_pk_bf16_f32 v120, v1, v2
	v_cvt_pk_bf16_f32 v121, v3, v93
	global_store_dwordx2 v85, v[120:121], s[98:99] offset:1024
	v_mul_f32_e32 v1, v16, v94
	v_mul_f32_e32 v2, v17, v94
	v_mul_f32_e32 v3, v18, v94
	v_mul_f32_e32 v93, v19, v94
	v_fma_f32 v1, v80, v1, v112
	v_fma_f32 v2, v81, v2, v113
	v_fma_f32 v3, v82, v3, v114
	v_fma_f32 v93, v83, v93, v115
	v_cvt_pk_bf16_f32 v96, v1, v2
	v_cvt_pk_bf16_f32 v97, v3, v93
	global_store_dwordx2 v85, v[96:97], s[98:99] offset:1536
	s_add_i32 s1, s0, 4
	s_min_i32 s1, s1, s11
	s_add_i32 s8, s1, 0xffff0000
	s_cmp_gt_i32 s1, 0xffff
	s_cselect_b32 s1, s8, s1
	s_cselect_b32 s2, s33, s48
	s_cselect_b32 s3, s37, s49
	s_lshl_b32 s8, s1, 12
	s_add_u32 s2, s2, s8
	s_addc_u32 s3, s3, 0
	global_load_dwordx4 v[4:7], v84, s[2:3] nt
	global_load_dwordx4 v[8:11], v84, s[2:3] offset:1024 nt
	global_load_dwordx4 v[12:15], v84, s[2:3] offset:2048 nt
	global_load_dwordx4 v[16:19], v84, s[2:3] offset:3072 nt
	s_add_i32 s0, s0, 1

.LnormQ2_l1_go:
	s_waitcnt vmcnt(24)
	v_mul_f32_e32 v92, v20, v20
	v_fmac_f32_e32 v92, v21, v21
	v_mul_f32_e32 v95, v22, v22
	v_fmac_f32_e32 v95, v23, v23
	v_add_f32_e32 v92, v92, v95
	v_mul_f32_e32 v93, v24, v24
	v_fmac_f32_e32 v93, v25, v25
	v_mul_f32_e32 v95, v26, v26
	v_fmac_f32_e32 v95, v27, v27
	v_add_f32_e32 v93, v93, v95
	v_add_f32_e32 v92, v92, v93
	v_mul_f32_e32 v93, v28, v28
	v_fmac_f32_e32 v93, v29, v29
	v_mul_f32_e32 v95, v30, v30
	v_fmac_f32_e32 v95, v31, v31
	v_add_f32_e32 v93, v93, v95
	v_add_f32_e32 v92, v92, v93
	v_mul_f32_e32 v93, v32, v32
	v_fmac_f32_e32 v93, v33, v33
	v_mul_f32_e32 v95, v34, v34
	v_fmac_f32_e32 v95, v35, v35
	v_add_f32_e32 v93, v93, v95
	v_add_f32_e32 v92, v92, v93
	ds_bpermute_b32 v93, v86, v92
	s_waitcnt lgkmcnt(0)
	v_add_f32_e32 v92, v92, v93
	ds_bpermute_b32 v93, v87, v92
	s_waitcnt lgkmcnt(0)
	v_add_f32_e32 v92, v92, v93
	ds_bpermute_b32 v93, v88, v92
	s_waitcnt lgkmcnt(0)
	v_add_f32_e32 v92, v92, v93
	ds_bpermute_b32 v93, v89, v92
	s_waitcnt lgkmcnt(0)
	v_add_f32_e32 v92, v92, v93
	ds_bpermute_b32 v93, v90, v92
	s_waitcnt lgkmcnt(0)
	v_add_f32_e32 v92, v92, v93
	ds_bpermute_b32 v93, v91, v92
	s_waitcnt lgkmcnt(0)
	v_add_f32_e32 v92, v92, v93
	v_fmamk_f32 v92, v92, 0x3a800000, v206
	v_rsq_f32_e32 v94, v92
	s_lshl_b32 s1, s0, 11
	s_add_u32 s98, s96, s1
	s_addc_u32 s99, s12, 0
	v_mul_f32_e32 v1, v20, v94
	v_mul_f32_e32 v2, v21, v94
	v_mul_f32_e32 v3, v22, v94
	v_mul_f32_e32 v93, v23, v94
	v_fma_f32 v1, v68, v1, v100
	v_fma_f32 v2, v69, v2, v101
	v_fma_f32 v3, v70, v3, v102
	v_fma_f32 v93, v71, v93, v103
	v_cvt_pk_bf16_f32 v116, v1, v2
	v_cvt_pk_bf16_f32 v117, v3, v93
	global_store_dwordx2 v85, v[116:117], s[98:99]
	v_mul_f32_e32 v1, v24, v94
	v_mul_f32_e32 v2, v25, v94
	v_mul_f32_e32 v3, v26, v94
	v_mul_f32_e32 v93, v27, v94
	v_fma_f32 v1, v72, v1, v104
	v_fma_f32 v2, v73, v2, v105
	v_fma_f32 v3, v74, v3, v106
	v_fma_f32 v93, v75, v93, v107
	v_cvt_pk_bf16_f32 v118, v1, v2
	v_cvt_pk_bf16_f32 v119, v3, v93
	global_store_dwordx2 v85, v[118:119], s[98:99] offset:512
	v_mul_f32_e32 v1, v28, v94
	v_mul_f32_e32 v2, v29, v94
	v_mul_f32_e32 v3, v30, v94
	v_mul_f32_e32 v93, v31, v94
	v_fma_f32 v1, v76, v1, v108
	v_fma_f32 v2, v77, v2, v109
	v_fma_f32 v3, v78, v3, v110
	v_fma_f32 v93, v79, v93, v111
	v_cvt_pk_bf16_f32 v120, v1, v2
	v_cvt_pk_bf16_f32 v121, v3, v93
	global_store_dwordx2 v85, v[120:121], s[98:99] offset:1024
	v_mul_f32_e32 v1, v32, v94
	v_mul_f32_e32 v2, v33, v94
	v_mul_f32_e32 v3, v34, v94
	v_mul_f32_e32 v93, v35, v94
	v_fma_f32 v1, v80, v1, v112
	v_fma_f32 v2, v81, v2, v113
	v_fma_f32 v3, v82, v3, v114
	v_fma_f32 v93, v83, v93, v115
	v_cvt_pk_bf16_f32 v96, v1, v2
	v_cvt_pk_bf16_f32 v97, v3, v93
	global_store_dwordx2 v85, v[96:97], s[98:99] offset:1536
	s_add_i32 s1, s0, 4
	s_min_i32 s1, s1, s11
	s_add_i32 s8, s1, 0xffff0000
	s_cmp_gt_i32 s1, 0xffff
	s_cselect_b32 s1, s8, s1
	s_cselect_b32 s2, s33, s48
	s_cselect_b32 s3, s37, s49
	s_lshl_b32 s8, s1, 12
	s_add_u32 s2, s2, s8
	s_addc_u32 s3, s3, 0
	global_load_dwordx4 v[20:23], v84, s[2:3] nt
	global_load_dwordx4 v[24:27], v84, s[2:3] offset:1024 nt
	global_load_dwordx4 v[28:31], v84, s[2:3] offset:2048 nt
	global_load_dwordx4 v[32:35], v84, s[2:3] offset:3072 nt
	s_add_i32 s0, s0, 1

.LnormQ2_l2_go:
	s_waitcnt vmcnt(24)
	v_mul_f32_e32 v92, v36, v36
	v_fmac_f32_e32 v92, v37, v37
	v_mul_f32_e32 v95, v38, v38
	v_fmac_f32_e32 v95, v39, v39
	v_add_f32_e32 v92, v92, v95
	v_mul_f32_e32 v93, v40, v40
	v_fmac_f32_e32 v93, v41, v41
	v_mul_f32_e32 v95, v42, v42
	v_fmac_f32_e32 v95, v43, v43
	v_add_f32_e32 v93, v93, v95
	v_add_f32_e32 v92, v92, v93
	v_mul_f32_e32 v93, v44, v44
	v_fmac_f32_e32 v93, v45, v45
	v_mul_f32_e32 v95, v46, v46
	v_fmac_f32_e32 v95, v47, v47
	v_add_f32_e32 v93, v93, v95
	v_add_f32_e32 v92, v92, v93
	v_mul_f32_e32 v93, v48, v48
	v_fmac_f32_e32 v93, v49, v49
	v_mul_f32_e32 v95, v50, v50
	v_fmac_f32_e32 v95, v51, v51
	v_add_f32_e32 v93, v93, v95
	v_add_f32_e32 v92, v92, v93
	ds_bpermute_b32 v93, v86, v92
	s_waitcnt lgkmcnt(0)
	v_add_f32_e32 v92, v92, v93
	ds_bpermute_b32 v93, v87, v92
	s_waitcnt lgkmcnt(0)
	v_add_f32_e32 v92, v92, v93
	ds_bpermute_b32 v93, v88, v92
	s_waitcnt lgkmcnt(0)
	v_add_f32_e32 v92, v92, v93
	ds_bpermute_b32 v93, v89, v92
	s_waitcnt lgkmcnt(0)
	v_add_f32_e32 v92, v92, v93
	ds_bpermute_b32 v93, v90, v92
	s_waitcnt lgkmcnt(0)
	v_add_f32_e32 v92, v92, v93
	ds_bpermute_b32 v93, v91, v92
	s_waitcnt lgkmcnt(0)
	v_add_f32_e32 v92, v92, v93
	v_fmamk_f32 v92, v92, 0x3a800000, v206
	v_rsq_f32_e32 v94, v92
	s_lshl_b32 s1, s0, 11
	s_add_u32 s98, s96, s1
	s_addc_u32 s99, s12, 0
	v_mul_f32_e32 v1, v36, v94
	v_mul_f32_e32 v2, v37, v94
	v_mul_f32_e32 v3, v38, v94
	v_mul_f32_e32 v93, v39, v94
	v_fma_f32 v1, v68, v1, v100
	v_fma_f32 v2, v69, v2, v101
	v_fma_f32 v3, v70, v3, v102
	v_fma_f32 v93, v71, v93, v103
	v_cvt_pk_bf16_f32 v116, v1, v2
	v_cvt_pk_bf16_f32 v117, v3, v93
	global_store_dwordx2 v85, v[116:117], s[98:99]
	v_mul_f32_e32 v1, v40, v94
	v_mul_f32_e32 v2, v41, v94
	v_mul_f32_e32 v3, v42, v94
	v_mul_f32_e32 v93, v43, v94
	v_fma_f32 v1, v72, v1, v104
	v_fma_f32 v2, v73, v2, v105
	v_fma_f32 v3, v74, v3, v106
	v_fma_f32 v93, v75, v93, v107
	v_cvt_pk_bf16_f32 v118, v1, v2
	v_cvt_pk_bf16_f32 v119, v3, v93
	global_store_dwordx2 v85, v[118:119], s[98:99] offset:512
	v_mul_f32_e32 v1, v44, v94
	v_mul_f32_e32 v2, v45, v94
	v_mul_f32_e32 v3, v46, v94
	v_mul_f32_e32 v93, v47, v94
	v_fma_f32 v1, v76, v1, v108
	v_fma_f32 v2, v77, v2, v109
	v_fma_f32 v3, v78, v3, v110
	v_fma_f32 v93, v79, v93, v111
	v_cvt_pk_bf16_f32 v120, v1, v2
	v_cvt_pk_bf16_f32 v121, v3, v93
	global_store_dwordx2 v85, v[120:121], s[98:99] offset:1024
	v_mul_f32_e32 v1, v48, v94
	v_mul_f32_e32 v2, v49, v94
	v_mul_f32_e32 v3, v50, v94
	v_mul_f32_e32 v93, v51, v94
	v_fma_f32 v1, v80, v1, v112
	v_fma_f32 v2, v81, v2, v113
	v_fma_f32 v3, v82, v3, v114
	v_fma_f32 v93, v83, v93, v115
	v_cvt_pk_bf16_f32 v96, v1, v2
	v_cvt_pk_bf16_f32 v97, v3, v93
	global_store_dwordx2 v85, v[96:97], s[98:99] offset:1536
	s_add_i32 s1, s0, 4
	s_min_i32 s1, s1, s11
	s_add_i32 s8, s1, 0xffff0000
	s_cmp_gt_i32 s1, 0xffff
	s_cselect_b32 s1, s8, s1
	s_cselect_b32 s2, s33, s48
	s_cselect_b32 s3, s37, s49
	s_lshl_b32 s8, s1, 12
	s_add_u32 s2, s2, s8
	s_addc_u32 s3, s3, 0
	global_load_dwordx4 v[36:39], v84, s[2:3] nt
	global_load_dwordx4 v[40:43], v84, s[2:3] offset:1024 nt
	global_load_dwordx4 v[44:47], v84, s[2:3] offset:2048 nt
	global_load_dwordx4 v[48:51], v84, s[2:3] offset:3072 nt
	s_add_i32 s0, s0, 1

.LnormQ2_l3_go:
	s_waitcnt vmcnt(24)
	v_mul_f32_e32 v92, v52, v52
	v_fmac_f32_e32 v92, v53, v53
	v_mul_f32_e32 v95, v54, v54
	v_fmac_f32_e32 v95, v55, v55
	v_add_f32_e32 v92, v92, v95
	v_mul_f32_e32 v93, v56, v56
	v_fmac_f32_e32 v93, v57, v57
	v_mul_f32_e32 v95, v58, v58
	v_fmac_f32_e32 v95, v59, v59
	v_add_f32_e32 v93, v93, v95
	v_add_f32_e32 v92, v92, v93
	v_mul_f32_e32 v93, v60, v60
	v_fmac_f32_e32 v93, v61, v61
	v_mul_f32_e32 v95, v62, v62
	v_fmac_f32_e32 v95, v63, v63
	v_add_f32_e32 v93, v93, v95
	v_add_f32_e32 v92, v92, v93
	v_mul_f32_e32 v93, v64, v64
	v_fmac_f32_e32 v93, v65, v65
	v_mul_f32_e32 v95, v66, v66
	v_fmac_f32_e32 v95, v67, v67
	v_add_f32_e32 v93, v93, v95
	v_add_f32_e32 v92, v92, v93
	ds_bpermute_b32 v93, v86, v92
	s_waitcnt lgkmcnt(0)
	v_add_f32_e32 v92, v92, v93
	ds_bpermute_b32 v93, v87, v92
	s_waitcnt lgkmcnt(0)
	v_add_f32_e32 v92, v92, v93
	ds_bpermute_b32 v93, v88, v92
	s_waitcnt lgkmcnt(0)
	v_add_f32_e32 v92, v92, v93
	ds_bpermute_b32 v93, v89, v92
	s_waitcnt lgkmcnt(0)
	v_add_f32_e32 v92, v92, v93
	ds_bpermute_b32 v93, v90, v92
	s_waitcnt lgkmcnt(0)
	v_add_f32_e32 v92, v92, v93
	ds_bpermute_b32 v93, v91, v92
	s_waitcnt lgkmcnt(0)
	v_add_f32_e32 v92, v92, v93
	v_fmamk_f32 v92, v92, 0x3a800000, v206
	v_rsq_f32_e32 v94, v92
	s_lshl_b32 s1, s0, 11
	s_add_u32 s98, s96, s1
	s_addc_u32 s99, s12, 0
	v_mul_f32_e32 v1, v52, v94
	v_mul_f32_e32 v2, v53, v94
	v_mul_f32_e32 v3, v54, v94
	v_mul_f32_e32 v93, v55, v94
	v_fma_f32 v1, v68, v1, v100
	v_fma_f32 v2, v69, v2, v101
	v_fma_f32 v3, v70, v3, v102
	v_fma_f32 v93, v71, v93, v103
	v_cvt_pk_bf16_f32 v116, v1, v2
	v_cvt_pk_bf16_f32 v117, v3, v93
	global_store_dwordx2 v85, v[116:117], s[98:99]
	v_mul_f32_e32 v1, v56, v94
	v_mul_f32_e32 v2, v57, v94
	v_mul_f32_e32 v3, v58, v94
	v_mul_f32_e32 v93, v59, v94
	v_fma_f32 v1, v72, v1, v104
	v_fma_f32 v2, v73, v2, v105
	v_fma_f32 v3, v74, v3, v106
	v_fma_f32 v93, v75, v93, v107
	v_cvt_pk_bf16_f32 v118, v1, v2
	v_cvt_pk_bf16_f32 v119, v3, v93
	global_store_dwordx2 v85, v[118:119], s[98:99] offset:512
	v_mul_f32_e32 v1, v60, v94
	v_mul_f32_e32 v2, v61, v94
	v_mul_f32_e32 v3, v62, v94
	v_mul_f32_e32 v93, v63, v94
	v_fma_f32 v1, v76, v1, v108
	v_fma_f32 v2, v77, v2, v109
	v_fma_f32 v3, v78, v3, v110
	v_fma_f32 v93, v79, v93, v111
	v_cvt_pk_bf16_f32 v120, v1, v2
	v_cvt_pk_bf16_f32 v121, v3, v93
	global_store_dwordx2 v85, v[120:121], s[98:99] offset:1024
	v_mul_f32_e32 v1, v64, v94
	v_mul_f32_e32 v2, v65, v94
	v_mul_f32_e32 v3, v66, v94
	v_mul_f32_e32 v93, v67, v94
	v_fma_f32 v1, v80, v1, v112
	v_fma_f32 v2, v81, v2, v113
	v_fma_f32 v3, v82, v3, v114
	v_fma_f32 v93, v83, v93, v115
	v_cvt_pk_bf16_f32 v96, v1, v2
	v_cvt_pk_bf16_f32 v97, v3, v93
	global_store_dwordx2 v85, v[96:97], s[98:99] offset:1536
	s_add_i32 s1, s0, 4
	s_min_i32 s1, s1, s11
	s_add_i32 s8, s1, 0xffff0000
	s_cmp_gt_i32 s1, 0xffff
	s_cselect_b32 s1, s8, s1
	s_cselect_b32 s2, s33, s48
	s_cselect_b32 s3, s37, s49
	s_lshl_b32 s8, s1, 12
	s_add_u32 s2, s2, s8
	s_addc_u32 s3, s3, 0
	global_load_dwordx4 v[52:55], v84, s[2:3] nt
	global_load_dwordx4 v[56:59], v84, s[2:3] offset:1024 nt
	global_load_dwordx4 v[60:63], v84, s[2:3] offset:2048 nt
	global_load_dwordx4 v[64:67], v84, s[2:3] offset:3072 nt
	s_add_i32 s0, s0, 1
	s_branch .LnormQ2_loop
.LnormQ2_done:
	s_waitcnt vmcnt(0)
	s_mov_b64 s[22:23], 0x1000
	s_mov_b64 s[0:1], -1
	s_branch .Lq_done
.Lq_to_pass2:
	v_mov_b32_e32 v5, 2
	ds_write_b32 v4, v5
	s_mov_b32 s98, s48
	s_mov_b32 s48, s33
	s_mov_b32 s33, s98
	s_mov_b32 s98, s49
	s_mov_b32 s49, s37
	s_mov_b32 s37, s98
	s_mov_b32 s65, s69
	s_mov_b32 s68, s70
	s_add_u32 s34, s34, 0x16000000
	s_addc_u32 s35, s35, 0
	s_mov_b32 s72, 0x800
	s_movk_i32 s71, 8
	s_movk_i32 s84, 32
	s_cmp_eq_u32 s4, 0
	s_cselect_b32 s6, 0x1800, 0
	s_add_i32 s6, s6, 0x12000
	v_mov_b32_e32 v14, v207
	s_branch .Lq_dn
.Lq_done:
	s_cbranch_vccnz .LBB0_215
	v_readlane_b32 s0, v255, 4
	v_readlane_b32 s1, v255, 5
	s_andn2_b64 vcc, exec, s[0:1]
	s_cbranch_vccnz .LBB0_1072
	v_mov_b32_e32 v1, v207
	v_readlane_b32 s1, v252, 34
	v_readfirstlane_b32 s0, v1
	s_ashr_i32 s0, s0, 6
	s_add_i32 s0, s0, s1
	v_readlane_b32 s1, v254, 22
	s_mul_i32 s0, s1, s0
	s_add_i32 s1, s0, s1
	s_min_i32 s4, s1, 0x10800
	v_mov_b32_e32 v4, 0x20184
	ds_read_b32 v5, v4
	s_waitcnt lgkmcnt(0)
	s_barrier
	v_readfirstlane_b32 s98, v5
	s_cmp_eq_u32 s98, 0
	s_cbranch_scc1 .Lq_h2
	v_mov_b32_e32 v5, 0
	ds_write_b32 v4, v5
	s_branch .LBB0_426
.Lq_h2:
	s_cmp_ge_i32 s0, s4
	s_cbranch_scc1 .LBB0_426
	s_add_i32 s5, s4, -1
	s_ashr_i32 s1, s0, 31
	s_add_i32 s2, s0, 0xffff0000
	s_cmp_gt_i32 s0, 0xffff
	s_cselect_b32 s3, 0, s1
	s_cselect_b32 s2, s2, s0
	s_cselect_b32 s6, s37, s49
	s_cselect_b32 s7, s33, s48
	s_lshl_b64 s[2:3], s[2:3], 12
	v_and_b32_e32 v84, 63, v1
	s_add_u32 s2, s7, s2
	s_addc_u32 s3, s6, s3
	v_lshlrev_b32_e32 v2, 4, v84
	global_load_dwordx4 v[32:35], v2, s[2:3] nt
	global_load_dwordx4 v[28:31], v2, s[2:3] offset:1024 nt
	global_load_dwordx4 v[4:7], v2, s[2:3] offset:2048 nt
	global_load_dwordx4 v[24:27], v2, s[2:3] offset:3072 nt
	s_add_i32 s2, s0, 1
	s_min_i32 s2, s2, s5
	s_ashr_i32 s3, s2, 31
	s_add_i32 s6, s2, 0xffff0000
	s_cmp_gt_i32 s2, 0xffff
	s_cselect_b32 s3, 0, s3
	s_cselect_b32 s2, s6, s2
	s_cselect_b32 s6, s37, s49
	s_cselect_b32 s7, s33, s48
	s_lshl_b64 s[2:3], s[2:3], 12
	s_add_u32 s2, s7, s2
	s_addc_u32 s3, s6, s3
	global_load_dwordx4 v[16:19], v2, s[2:3] offset:3072 nt
	global_load_dwordx4 v[8:11], v2, s[2:3] offset:2048 nt
	global_load_dwordx4 v[12:15], v2, s[2:3] offset:1024 nt
	global_load_dwordx4 v[20:23], v2, s[2:3] nt
	v_readlane_b32 s6, v253, 23
	v_mov_b32_e32 v3, v0
	v_readlane_b32 s7, v253, 24
	v_mbcnt_hi_u32_b32 v1, -1, v232
	s_mov_b32 s2, -1
	v_lshl_add_u64 v[86:87], s[6:7], 0, v[2:3]
	v_and_b32_e32 v2, 64, v1
	v_add_u32_e32 v2, 64, v2
	v_xor_b32_e32 v3, 1, v1
	v_cmp_lt_i32_e32 vcc, v3, v2
	s_lshl_b64 s[6:7], s[0:1], 11
	s_add_u32 s6, s96, s6
	v_cndmask_b32_e32 v3, v1, v3, vcc
	v_lshlrev_b32_e32 v85, 2, v3
	v_xor_b32_e32 v3, 2, v1
	v_cmp_lt_i32_e32 vcc, v3, v2
	v_readlane_b32 s1, v252, 53
	s_addc_u32 s7, s1, s7
	v_cndmask_b32_e32 v3, v1, v3, vcc
	v_lshlrev_b32_e32 v90, 2, v3
	v_xor_b32_e32 v3, 4, v1
	v_cmp_lt_i32_e32 vcc, v3, v2
	s_waitcnt vmcnt(4)
	v_mov_b32_e32 v95, v25
	v_cndmask_b32_e32 v3, v1, v3, vcc
	v_lshlrev_b32_e32 v91, 2, v3
	v_xor_b32_e32 v3, 8, v1
	v_cmp_lt_i32_e32 vcc, v3, v2
	v_mov_b32_e32 v96, v26
	v_mov_b32_e32 v97, v27
	v_cndmask_b32_e32 v3, v1, v3, vcc
	v_lshlrev_b32_e32 v92, 2, v3
	v_xor_b32_e32 v3, 16, v1
	v_cmp_lt_i32_e32 vcc, v3, v2
	s_nop 1
	v_cndmask_b32_e32 v3, v1, v3, vcc
	v_lshlrev_b32_e32 v93, 2, v3
	v_xor_b32_e32 v3, 32, v1
	v_cmp_lt_i32_e32 vcc, v3, v2
	v_lshlrev_b32_e32 v2, 3, v84
	s_nop 0
	v_cndmask_b32_e32 v1, v1, v3, vcc
	v_mov_b32_e32 v3, v0
	v_lshl_add_u64 v[88:89], s[6:7], 0, v[2:3]
	v_mov_b32_e32 v2, v0
	v_lshlrev_b32_e32 v94, 2, v1
	v_mov_b32_e32 v1, v0
	v_mov_b64_e32 v[78:79], v[2:3]
	v_mov_b64_e32 v[70:71], v[2:3]
	v_mov_b64_e32 v[50:51], v[2:3]
	v_mov_b64_e32 v[38:39], v[2:3]
	v_mov_b64_e32 v[82:83], v[2:3]
	v_mov_b64_e32 v[74:75], v[2:3]
	v_mov_b64_e32 v[54:55], v[2:3]
	v_mov_b64_e32 v[42:43], v[2:3]
	v_mov_b64_e32 v[76:77], v[0:1]
	v_mov_b64_e32 v[68:69], v[0:1]
	v_mov_b64_e32 v[48:49], v[0:1]
	v_mov_b64_e32 v[36:37], v[0:1]
	v_mov_b64_e32 v[80:81], v[0:1]
	v_mov_b64_e32 v[72:73], v[0:1]
	v_mov_b64_e32 v[52:53], v[0:1]
	v_mov_b64_e32 v[40:41], v[0:1]
	v_mov_b32_e32 v1, v24
	s_branch .LBB0_424

.LBB0_1072:
	v_readlane_b32 s0, v254, 39
	v_readlane_b32 s1, v254, 40
	s_andn2_b64 vcc, exec, s[0:1]
	s_cbranch_vccnz .LBB0_214
	v_mov_b32_e32 v1, v207
	v_readlane_b32 s1, v252, 34
	v_readfirstlane_b32 s0, v1
	s_ashr_i32 s0, s0, 6
	s_add_i32 s0, s0, s1
	v_readlane_b32 s1, v254, 22
	s_mul_i32 s0, s1, s0
	s_add_i32 s1, s0, s1
	s_min_i32 s4, s1, 0x10800
	v_mov_b32_e32 v4, 0x20184
	ds_read_b32 v5, v4
	s_waitcnt lgkmcnt(0)
	s_barrier
	v_readfirstlane_b32 s98, v5
	s_cmp_eq_u32 s98, 0
	s_cbranch_scc1 .Lq_h3
	v_mov_b32_e32 v5, 0
	ds_write_b32 v4, v5
	s_branch .LBB0_1078
.Lq_h3:
	s_cmp_ge_i32 s0, s4
	s_cbranch_scc1 .LBB0_1078
	s_add_i32 s5, s4, -1
	s_ashr_i32 s1, s0, 31
	s_add_i32 s2, s0, 0xffff0000
	s_cmp_gt_i32 s0, 0xffff
	s_cselect_b32 s3, 0, s1
	s_cselect_b32 s2, s2, s0
	s_cselect_b32 s6, s37, s49
	s_cselect_b32 s7, s33, s48
	s_lshl_b64 s[2:3], s[2:3], 12
	v_and_b32_e32 v84, 63, v1
	s_add_u32 s2, s7, s2
	s_addc_u32 s3, s6, s3
	v_lshlrev_b32_e32 v2, 4, v84
	global_load_dwordx4 v[32:35], v2, s[2:3] nt
	global_load_dwordx4 v[28:31], v2, s[2:3] offset:1024 nt
	global_load_dwordx4 v[4:7], v2, s[2:3] offset:2048 nt
	global_load_dwordx4 v[24:27], v2, s[2:3] offset:3072 nt
	s_add_i32 s2, s0, 1
	s_min_i32 s2, s2, s5
	s_ashr_i32 s3, s2, 31
	s_add_i32 s6, s2, 0xffff0000
	s_cmp_gt_i32 s2, 0xffff
	s_cselect_b32 s3, 0, s3
	s_cselect_b32 s2, s6, s2
	s_cselect_b32 s6, s37, s49
	s_cselect_b32 s7, s33, s48
	s_lshl_b64 s[2:3], s[2:3], 12
	s_add_u32 s2, s7, s2
	s_addc_u32 s3, s6, s3
	global_load_dwordx4 v[16:19], v2, s[2:3] offset:3072 nt
	global_load_dwordx4 v[8:11], v2, s[2:3] offset:2048 nt
	global_load_dwordx4 v[12:15], v2, s[2:3] offset:1024 nt
	global_load_dwordx4 v[20:23], v2, s[2:3] nt
	v_cmp_lt_i32_e32 vcc, v228, v235
	v_readlane_b32 s6, v253, 41
	v_mov_b32_e32 v3, v0
	v_cndmask_b32_e32 v1, v233, v228, vcc
	v_cmp_lt_i32_e32 vcc, v234, v235
	v_readlane_b32 s7, v253, 42
	v_lshlrev_b32_e32 v85, 2, v1
	v_cndmask_b32_e32 v1, v233, v234, vcc
	v_cmp_lt_i32_e32 vcc, v240, v235
	v_lshl_add_u64 v[86:87], s[6:7], 0, v[2:3]
	v_lshlrev_b32_e32 v90, 2, v1
	v_cndmask_b32_e32 v1, v233, v240, vcc
	v_cmp_lt_i32_e32 vcc, v245, v235
	s_lshl_b64 s[6:7], s[0:1], 11
	v_lshlrev_b32_e32 v91, 2, v1
	v_cndmask_b32_e32 v1, v233, v245, vcc
	v_cmp_lt_i32_e32 vcc, v246, v235
	s_add_u32 s6, s96, s6
	v_readlane_b32 s1, v252, 53
	v_lshlrev_b32_e32 v92, 2, v1
	v_cndmask_b32_e32 v1, v233, v246, vcc
	v_cmp_lt_i32_e32 vcc, v241, v235
	v_lshlrev_b32_e32 v2, 3, v84
	s_addc_u32 s7, s1, s7
	v_lshlrev_b32_e32 v93, 2, v1
	v_cndmask_b32_e32 v1, v233, v241, vcc
	v_lshl_add_u64 v[88:89], s[6:7], 0, v[2:3]
	v_mov_b32_e32 v2, v0
	v_lshlrev_b32_e32 v94, 2, v1
	v_mov_b32_e32 v1, v0
	v_mov_b64_e32 v[78:79], v[2:3]
	v_mov_b64_e32 v[70:71], v[2:3]
	v_mov_b64_e32 v[50:51], v[2:3]
	v_mov_b64_e32 v[38:39], v[2:3]
	v_mov_b64_e32 v[82:83], v[2:3]
	v_mov_b64_e32 v[74:75], v[2:3]
	v_mov_b64_e32 v[54:55], v[2:3]
	v_mov_b64_e32 v[42:43], v[2:3]
	s_mov_b32 s2, -1
	v_mov_b64_e32 v[76:77], v[0:1]
	v_mov_b64_e32 v[68:69], v[0:1]
	v_mov_b64_e32 v[48:49], v[0:1]
	v_mov_b64_e32 v[36:37], v[0:1]
	v_mov_b64_e32 v[80:81], v[0:1]
	v_mov_b64_e32 v[72:73], v[0:1]
	v_mov_b64_e32 v[52:53], v[0:1]
	v_mov_b64_e32 v[40:41], v[0:1]
	s_waitcnt vmcnt(4)
	v_mov_b32_e32 v1, v24
	v_mov_b32_e32 v95, v25
	v_mov_b32_e32 v96, v26
	v_mov_b32_e32 v97, v27
	s_branch .LBB0_1076
